# EpiResid epilogues of G2/G4/G6/G8: the 16 residual loads issued together at the epilogue start instead of load-wait pairs
# baseline (speedup 1.0000x reference)
.LBB0_669:
	v_lshl_add_u32 v146, s36, 8, v148
	v_ashrrev_i32_e32 v147, 31, v146
	v_lshl_add_u32 v144, s6, 8, v150
	v_lshlrev_b64 v[156:157], 11, v[146:147]
	v_ashrrev_i32_e32 v145, 31, v144
	v_lshl_add_u32 v174, v144, 1, v156
	global_load_dwordx4 v[170:173], v174, s[34:35]
	s_nop 0
	global_load_dwordx4 v[174:177], v174, s[34:35] offset:256
	v_lshl_add_u32 v182, v144, 1, v156
	v_add_u32_e32 v182, 0x8000, v182
	global_load_dwordx4 v[178:181], v182, s[34:35]
	s_nop 0
	global_load_dwordx4 v[182:185], v182, s[34:35] offset:256
	v_lshl_add_u32 v190, v144, 1, v156
	v_add_u32_e32 v190, 0x10000, v190
	global_load_dwordx4 v[186:189], v190, s[34:35]
	s_nop 0
	global_load_dwordx4 v[190:193], v190, s[34:35] offset:256
	v_lshl_add_u32 v204, v144, 1, v156
	v_add_u32_e32 v204, 0x18000, v204
	global_load_dwordx4 v[200:203], v204, s[34:35]
	s_nop 0
	global_load_dwordx4 v[204:207], v204, s[34:35] offset:256
	v_lshl_add_u32 v212, v144, 1, v156
	v_add_u32_e32 v212, 0x40000, v212
	global_load_dwordx4 v[208:211], v212, s[34:35]
	s_nop 0
	global_load_dwordx4 v[212:215], v212, s[34:35] offset:256
	v_lshl_add_u32 v220, v144, 1, v156
	v_add_u32_e32 v220, 0x48000, v220
	global_load_dwordx4 v[216:219], v220, s[34:35]
	s_nop 0
	global_load_dwordx4 v[220:223], v220, s[34:35] offset:256
	v_lshl_add_u32 v228, v144, 1, v156
	v_add_u32_e32 v228, 0x50000, v228
	global_load_dwordx4 v[224:227], v228, s[34:35]
	s_nop 0
	global_load_dwordx4 v[228:231], v228, s[34:35] offset:256
	v_lshl_add_u32 v236, v144, 1, v156
	v_add_u32_e32 v236, 0x58000, v236
	global_load_dwordx4 v[232:235], v236, s[34:35]
	s_nop 0
	global_load_dwordx4 v[236:239], v236, s[34:35] offset:256
	v_lshl_add_u64 v[156:157], s[34:35], 0, v[156:157]
	v_lshl_add_u64 v[156:157], v[144:145], 1, v[156:157]
	s_lshl_b32 s36, s6, 2
	s_ashr_i32 s37, s36, 31
	s_waitcnt vmcnt(15)
	v_mov_b32_e32 v162, v170
	v_mov_b32_e32 v163, v171
	v_mov_b32_e32 v164, v172
	v_mov_b32_e32 v165, v173
	v_lshlrev_b32_e32 v166, 16, v162
	v_and_b32_e32 v167, 0xffff0000, v162
	v_lshlrev_b32_e32 v162, 16, v163
	v_and_b32_e32 v163, 0xffff0000, v163
	v_lshlrev_b32_e32 v168, 16, v164
	v_and_b32_e32 v169, 0xffff0000, v164
	v_lshlrev_b32_e32 v164, 16, v165
	v_and_b32_e32 v165, 0xffff0000, v165
	v_pk_add_f32 v[126:127], v[126:127], v[162:163]
	v_pk_add_f32 v[124:125], v[124:125], v[166:167]
	v_pk_add_f32 v[162:163], v[122:123], v[164:165]
	v_pk_add_f32 v[164:165], v[120:121], v[168:169]
	v_cvt_pk_bf16_f32 v120, v124, v125
	v_cvt_pk_bf16_f32 v121, v126, v127
	v_cvt_pk_bf16_f32 v122, v164, v165
	v_cvt_pk_bf16_f32 v123, v162, v163
	global_store_dwordx4 v[156:157], v[120:123], off
	s_nop 1
	v_mul_f32_e32 v120, v125, v125
	v_mul_f32_e32 v121, v127, v127
	v_fmac_f32_e32 v120, v124, v124
	v_fmac_f32_e32 v121, v126, v126
	v_add_f32_e32 v120, v120, v121
	v_mul_f32_e32 v121, v165, v165
	v_fmac_f32_e32 v121, v164, v164
	v_add_f32_e32 v120, v121, v120
	v_mul_f32_e32 v121, v163, v163
	v_fmac_f32_e32 v121, v162, v162
	v_add_f32_e32 v158, v121, v120
	s_waitcnt vmcnt(15)
	v_mov_b32_e32 v120, v174
	v_mov_b32_e32 v121, v175
	v_mov_b32_e32 v122, v176
	v_mov_b32_e32 v123, v177
	v_lshlrev_b32_e32 v124, 16, v120
	v_and_b32_e32 v125, 0xffff0000, v120
	v_lshlrev_b32_e32 v120, 16, v121
	v_and_b32_e32 v121, 0xffff0000, v121
	v_lshlrev_b32_e32 v126, 16, v122
	v_and_b32_e32 v127, 0xffff0000, v122
	v_lshlrev_b32_e32 v122, 16, v123
	v_and_b32_e32 v123, 0xffff0000, v123
	v_pk_add_f32 v[118:119], v[118:119], v[120:121]
	v_pk_add_f32 v[116:117], v[116:117], v[124:125]
	v_pk_add_f32 v[120:121], v[114:115], v[122:123]
	v_pk_add_f32 v[122:123], v[112:113], v[126:127]
	v_cvt_pk_bf16_f32 v112, v116, v117
	v_cvt_pk_bf16_f32 v113, v118, v119
	v_cvt_pk_bf16_f32 v114, v122, v123
	v_cvt_pk_bf16_f32 v115, v120, v121
	global_store_dwordx4 v[156:157], v[112:115], off offset:256
	s_nop 1
	v_mul_f32_e32 v112, v117, v117
	v_mul_f32_e32 v113, v119, v119
	v_fmac_f32_e32 v112, v116, v116
	v_fmac_f32_e32 v113, v118, v118
	v_add_f32_e32 v112, v112, v113
	v_mul_f32_e32 v113, v123, v123
	v_fmac_f32_e32 v113, v122, v122
	v_add_f32_e32 v112, v113, v112
	v_mul_f32_e32 v113, v121, v121
	v_fmac_f32_e32 v113, v120, v120
	v_add_f32_e32 v112, v113, v112
	v_add_f32_e32 v112, v158, v112
	ds_bpermute_b32 v113, v151, v112
	s_waitcnt lgkmcnt(0)
	v_add_f32_e32 v112, v112, v113
	ds_bpermute_b32 v113, v152, v112
	s_and_saveexec_b64 s[8:9], s[44:45]
	s_cbranch_execz .LBB0_671
	v_lshlrev_b64 v[114:115], 6, v[146:147]
	v_lshl_add_u64 v[114:115], s[0:1], 0, v[114:115]
	v_lshl_add_u64 v[114:115], s[36:37], 2, v[114:115]
	s_lshl_b32 s6, s18, 2
	v_lshl_add_u64 v[114:115], v[114:115], 0, s[6:7]
	s_waitcnt lgkmcnt(0)
	v_add_f32_e32 v112, v112, v113
	global_store_dword v[114:115], v112, off
.LBB0_671:
	s_or_b64 exec, exec, s[8:9]
	v_or_b32_e32 v112, 16, v146
	s_waitcnt lgkmcnt(0)
	v_ashrrev_i32_e32 v113, 31, v112
	v_lshlrev_b64 v[114:115], 11, v[112:113]
	v_lshl_add_u64 v[114:115], s[34:35], 0, v[114:115]
	v_lshl_add_u64 v[118:119], v[144:145], 1, v[114:115]
	s_waitcnt vmcnt(15)
	v_mov_b32_e32 v114, v178
	v_mov_b32_e32 v115, v179
	v_mov_b32_e32 v116, v180
	v_mov_b32_e32 v117, v181
	v_lshlrev_b32_e32 v120, 16, v114
	v_and_b32_e32 v121, 0xffff0000, v114
	v_lshlrev_b32_e32 v114, 16, v115
	v_and_b32_e32 v115, 0xffff0000, v115
	v_lshlrev_b32_e32 v122, 16, v116
	v_and_b32_e32 v123, 0xffff0000, v116
	v_lshlrev_b32_e32 v116, 16, v117
	v_and_b32_e32 v117, 0xffff0000, v117
	v_pk_add_f32 v[110:111], v[110:111], v[114:115]
	v_pk_add_f32 v[108:109], v[108:109], v[120:121]
	v_pk_add_f32 v[114:115], v[106:107], v[116:117]
	v_pk_add_f32 v[116:117], v[104:105], v[122:123]
	v_cvt_pk_bf16_f32 v104, v108, v109
	v_cvt_pk_bf16_f32 v105, v110, v111
	v_cvt_pk_bf16_f32 v106, v116, v117
	v_cvt_pk_bf16_f32 v107, v114, v115
	global_store_dwordx4 v[118:119], v[104:107], off
	s_nop 1
	v_mul_f32_e32 v104, v109, v109
	v_mul_f32_e32 v105, v111, v111
	v_fmac_f32_e32 v104, v108, v108
	v_fmac_f32_e32 v105, v110, v110
	v_add_f32_e32 v104, v104, v105
	v_mul_f32_e32 v105, v117, v117
	v_fmac_f32_e32 v105, v116, v116
	v_add_f32_e32 v104, v105, v104
	v_mul_f32_e32 v105, v115, v115
	v_fmac_f32_e32 v105, v114, v114
	v_add_f32_e32 v114, v105, v104
	s_waitcnt vmcnt(15)
	v_mov_b32_e32 v104, v182
	v_mov_b32_e32 v105, v183
	v_mov_b32_e32 v106, v184
	v_mov_b32_e32 v107, v185
	v_lshlrev_b32_e32 v108, 16, v104
	v_and_b32_e32 v109, 0xffff0000, v104
	v_lshlrev_b32_e32 v104, 16, v105
	v_and_b32_e32 v105, 0xffff0000, v105
	v_lshlrev_b32_e32 v110, 16, v106
	v_and_b32_e32 v111, 0xffff0000, v106
	v_lshlrev_b32_e32 v106, 16, v107
	v_and_b32_e32 v107, 0xffff0000, v107
	v_pk_add_f32 v[102:103], v[102:103], v[104:105]
	v_pk_add_f32 v[100:101], v[100:101], v[108:109]
	v_pk_add_f32 v[104:105], v[98:99], v[106:107]
	v_pk_add_f32 v[106:107], v[96:97], v[110:111]
	v_cvt_pk_bf16_f32 v96, v100, v101
	v_cvt_pk_bf16_f32 v97, v102, v103
	v_cvt_pk_bf16_f32 v98, v106, v107
	v_cvt_pk_bf16_f32 v99, v104, v105
	global_store_dwordx4 v[118:119], v[96:99], off offset:256
	s_nop 1
	v_mul_f32_e32 v96, v101, v101
	v_mul_f32_e32 v97, v103, v103
	v_fmac_f32_e32 v96, v100, v100
	v_fmac_f32_e32 v97, v102, v102
	v_add_f32_e32 v96, v96, v97
	v_mul_f32_e32 v97, v107, v107
	v_fmac_f32_e32 v97, v106, v106
	v_add_f32_e32 v96, v97, v96
	v_mul_f32_e32 v97, v105, v105
	v_fmac_f32_e32 v97, v104, v104
	v_add_f32_e32 v96, v97, v96
	v_add_f32_e32 v96, v114, v96
	ds_bpermute_b32 v97, v151, v96
	s_waitcnt lgkmcnt(0)
	v_add_f32_e32 v96, v96, v97
	ds_bpermute_b32 v97, v152, v96
	s_and_saveexec_b64 s[8:9], s[44:45]
	s_cbranch_execz .LBB0_673
	v_lshlrev_b64 v[98:99], 6, v[112:113]
	v_lshl_add_u64 v[98:99], s[0:1], 0, v[98:99]
	v_lshl_add_u64 v[98:99], s[36:37], 2, v[98:99]
	s_lshl_b32 s6, s18, 2
	v_lshl_add_u64 v[98:99], v[98:99], 0, s[6:7]
	s_waitcnt lgkmcnt(0)
	v_add_f32_e32 v96, v96, v97
	global_store_dword v[98:99], v96, off
.LBB0_673:
	s_or_b64 exec, exec, s[8:9]
	v_or_b32_e32 v96, 32, v146
	s_waitcnt lgkmcnt(0)
	v_ashrrev_i32_e32 v97, 31, v96
	v_lshlrev_b64 v[98:99], 11, v[96:97]
	v_lshl_add_u64 v[98:99], s[34:35], 0, v[98:99]
	v_lshl_add_u64 v[102:103], v[144:145], 1, v[98:99]
	s_waitcnt vmcnt(15)
	v_mov_b32_e32 v98, v186
	v_mov_b32_e32 v99, v187
	v_mov_b32_e32 v100, v188
	v_mov_b32_e32 v101, v189
	v_lshlrev_b32_e32 v104, 16, v98
	v_and_b32_e32 v105, 0xffff0000, v98
	v_lshlrev_b32_e32 v98, 16, v99
	v_and_b32_e32 v99, 0xffff0000, v99
	v_lshlrev_b32_e32 v106, 16, v100
	v_and_b32_e32 v107, 0xffff0000, v100
	v_lshlrev_b32_e32 v100, 16, v101
	v_and_b32_e32 v101, 0xffff0000, v101
	v_pk_add_f32 v[94:95], v[94:95], v[98:99]
	v_pk_add_f32 v[92:93], v[92:93], v[104:105]
	v_pk_add_f32 v[98:99], v[90:91], v[100:101]
	v_pk_add_f32 v[100:101], v[88:89], v[106:107]
	v_cvt_pk_bf16_f32 v88, v92, v93
	v_cvt_pk_bf16_f32 v89, v94, v95
	v_cvt_pk_bf16_f32 v90, v100, v101
	v_cvt_pk_bf16_f32 v91, v98, v99
	global_store_dwordx4 v[102:103], v[88:91], off
	s_nop 1
	v_mul_f32_e32 v88, v93, v93
	v_mul_f32_e32 v89, v95, v95
	v_fmac_f32_e32 v88, v92, v92
	v_fmac_f32_e32 v89, v94, v94
	v_add_f32_e32 v88, v88, v89
	v_mul_f32_e32 v89, v101, v101
	v_fmac_f32_e32 v89, v100, v100
	v_add_f32_e32 v88, v89, v88
	v_mul_f32_e32 v89, v99, v99
	v_fmac_f32_e32 v89, v98, v98
	v_add_f32_e32 v98, v89, v88
	s_waitcnt vmcnt(15)
	v_mov_b32_e32 v88, v190
	v_mov_b32_e32 v89, v191
	v_mov_b32_e32 v90, v192
	v_mov_b32_e32 v91, v193
	v_lshlrev_b32_e32 v92, 16, v88
	v_and_b32_e32 v93, 0xffff0000, v88
	v_lshlrev_b32_e32 v88, 16, v89
	v_and_b32_e32 v89, 0xffff0000, v89
	v_lshlrev_b32_e32 v94, 16, v90
	v_and_b32_e32 v95, 0xffff0000, v90
	v_lshlrev_b32_e32 v90, 16, v91
	v_and_b32_e32 v91, 0xffff0000, v91
	v_pk_add_f32 v[86:87], v[86:87], v[88:89]
	v_pk_add_f32 v[84:85], v[84:85], v[92:93]
	v_pk_add_f32 v[88:89], v[82:83], v[90:91]
	v_pk_add_f32 v[90:91], v[80:81], v[94:95]
	v_cvt_pk_bf16_f32 v80, v84, v85
	v_cvt_pk_bf16_f32 v81, v86, v87
	v_cvt_pk_bf16_f32 v82, v90, v91
	v_cvt_pk_bf16_f32 v83, v88, v89
	global_store_dwordx4 v[102:103], v[80:83], off offset:256
	s_nop 1
	v_mul_f32_e32 v80, v85, v85
	v_mul_f32_e32 v81, v87, v87
	v_fmac_f32_e32 v80, v84, v84
	v_fmac_f32_e32 v81, v86, v86
	v_add_f32_e32 v80, v80, v81
	v_mul_f32_e32 v81, v91, v91
	v_fmac_f32_e32 v81, v90, v90
	v_add_f32_e32 v80, v81, v80
	v_mul_f32_e32 v81, v89, v89
	v_fmac_f32_e32 v81, v88, v88
	v_add_f32_e32 v80, v81, v80
	v_add_f32_e32 v80, v98, v80
	ds_bpermute_b32 v81, v151, v80
	s_waitcnt lgkmcnt(0)
	v_add_f32_e32 v80, v80, v81
	ds_bpermute_b32 v81, v152, v80
	s_and_saveexec_b64 s[8:9], s[44:45]
	s_cbranch_execz .LBB0_675
	v_lshlrev_b64 v[82:83], 6, v[96:97]
	v_lshl_add_u64 v[82:83], s[0:1], 0, v[82:83]
	v_lshl_add_u64 v[82:83], s[36:37], 2, v[82:83]
	s_lshl_b32 s6, s18, 2
	v_lshl_add_u64 v[82:83], v[82:83], 0, s[6:7]
	s_waitcnt lgkmcnt(0)
	v_add_f32_e32 v80, v80, v81
	global_store_dword v[82:83], v80, off
.LBB0_675:
	s_or_b64 exec, exec, s[8:9]
	v_or_b32_e32 v80, 48, v146
	s_waitcnt lgkmcnt(0)
	v_ashrrev_i32_e32 v81, 31, v80
	v_lshlrev_b64 v[82:83], 11, v[80:81]
	v_lshl_add_u64 v[82:83], s[34:35], 0, v[82:83]
	v_lshl_add_u64 v[86:87], v[144:145], 1, v[82:83]
	s_waitcnt vmcnt(15)
	v_mov_b32_e32 v82, v200
	v_mov_b32_e32 v83, v201
	v_mov_b32_e32 v84, v202
	v_mov_b32_e32 v85, v203
	v_lshlrev_b32_e32 v88, 16, v82
	v_and_b32_e32 v89, 0xffff0000, v82
	v_lshlrev_b32_e32 v82, 16, v83
	v_and_b32_e32 v83, 0xffff0000, v83
	v_lshlrev_b32_e32 v90, 16, v84
	v_and_b32_e32 v91, 0xffff0000, v84
	v_lshlrev_b32_e32 v84, 16, v85
	v_and_b32_e32 v85, 0xffff0000, v85
	v_pk_add_f32 v[78:79], v[78:79], v[82:83]
	v_pk_add_f32 v[76:77], v[76:77], v[88:89]
	v_pk_add_f32 v[82:83], v[74:75], v[84:85]
	v_pk_add_f32 v[84:85], v[72:73], v[90:91]
	v_cvt_pk_bf16_f32 v72, v76, v77
	v_cvt_pk_bf16_f32 v73, v78, v79
	v_cvt_pk_bf16_f32 v74, v84, v85
	v_cvt_pk_bf16_f32 v75, v82, v83
	global_store_dwordx4 v[86:87], v[72:75], off
	s_nop 1
	v_mul_f32_e32 v72, v77, v77
	v_mul_f32_e32 v73, v79, v79
	v_fmac_f32_e32 v72, v76, v76
	v_fmac_f32_e32 v73, v78, v78
	v_add_f32_e32 v72, v72, v73
	v_mul_f32_e32 v73, v85, v85
	v_fmac_f32_e32 v73, v84, v84
	v_add_f32_e32 v72, v73, v72
	v_mul_f32_e32 v73, v83, v83
	v_fmac_f32_e32 v73, v82, v82
	v_add_f32_e32 v82, v73, v72
	s_waitcnt vmcnt(15)
	v_mov_b32_e32 v72, v204
	v_mov_b32_e32 v73, v205
	v_mov_b32_e32 v74, v206
	v_mov_b32_e32 v75, v207
	v_lshlrev_b32_e32 v76, 16, v72
	v_and_b32_e32 v77, 0xffff0000, v72
	v_lshlrev_b32_e32 v72, 16, v73
	v_and_b32_e32 v73, 0xffff0000, v73
	v_lshlrev_b32_e32 v78, 16, v74
	v_and_b32_e32 v79, 0xffff0000, v74
	v_lshlrev_b32_e32 v74, 16, v75
	v_and_b32_e32 v75, 0xffff0000, v75
	v_pk_add_f32 v[70:71], v[70:71], v[72:73]
	v_pk_add_f32 v[68:69], v[68:69], v[76:77]
	v_pk_add_f32 v[72:73], v[66:67], v[74:75]
	v_pk_add_f32 v[74:75], v[64:65], v[78:79]
	v_cvt_pk_bf16_f32 v64, v68, v69
	v_cvt_pk_bf16_f32 v65, v70, v71
	v_cvt_pk_bf16_f32 v66, v74, v75
	v_cvt_pk_bf16_f32 v67, v72, v73
	global_store_dwordx4 v[86:87], v[64:67], off offset:256
	s_nop 1
	v_mul_f32_e32 v64, v69, v69
	v_mul_f32_e32 v65, v71, v71
	v_fmac_f32_e32 v64, v68, v68
	v_fmac_f32_e32 v65, v70, v70
	v_add_f32_e32 v64, v64, v65
	v_mul_f32_e32 v65, v75, v75
	v_fmac_f32_e32 v65, v74, v74
	v_add_f32_e32 v64, v65, v64
	v_mul_f32_e32 v65, v73, v73
	v_fmac_f32_e32 v65, v72, v72
	v_add_f32_e32 v64, v65, v64
	v_add_f32_e32 v64, v82, v64
	ds_bpermute_b32 v65, v151, v64
	s_waitcnt lgkmcnt(0)
	v_add_f32_e32 v64, v64, v65
	ds_bpermute_b32 v65, v152, v64
	s_and_saveexec_b64 s[8:9], s[44:45]
	s_cbranch_execz .LBB0_677
	v_lshlrev_b64 v[66:67], 6, v[80:81]
	v_lshl_add_u64 v[66:67], s[0:1], 0, v[66:67]
	v_lshl_add_u64 v[66:67], s[36:37], 2, v[66:67]
	s_lshl_b32 s6, s18, 2
	v_lshl_add_u64 v[66:67], v[66:67], 0, s[6:7]
	s_waitcnt lgkmcnt(0)
	v_add_f32_e32 v64, v64, v65
	global_store_dword v[66:67], v64, off
.LBB0_677:
	s_or_b64 exec, exec, s[8:9]
	v_add_u32_e32 v64, 0x80, v146
	s_waitcnt lgkmcnt(0)
	v_ashrrev_i32_e32 v65, 31, v64
	v_lshlrev_b64 v[66:67], 11, v[64:65]
	v_lshl_add_u64 v[66:67], s[34:35], 0, v[66:67]
	v_lshl_add_u64 v[70:71], v[144:145], 1, v[66:67]
	s_waitcnt vmcnt(15)
	v_mov_b32_e32 v66, v208
	v_mov_b32_e32 v67, v209
	v_mov_b32_e32 v68, v210
	v_mov_b32_e32 v69, v211
	v_lshlrev_b32_e32 v72, 16, v66
	v_and_b32_e32 v73, 0xffff0000, v66
	v_lshlrev_b32_e32 v66, 16, v67
	v_and_b32_e32 v67, 0xffff0000, v67
	v_lshlrev_b32_e32 v74, 16, v68
	v_and_b32_e32 v75, 0xffff0000, v68
	v_lshlrev_b32_e32 v68, 16, v69
	v_and_b32_e32 v69, 0xffff0000, v69
	v_pk_add_f32 v[62:63], v[62:63], v[66:67]
	v_pk_add_f32 v[60:61], v[60:61], v[72:73]
	v_pk_add_f32 v[66:67], v[58:59], v[68:69]
	v_pk_add_f32 v[68:69], v[56:57], v[74:75]
	v_cvt_pk_bf16_f32 v56, v60, v61
	v_cvt_pk_bf16_f32 v57, v62, v63
	v_cvt_pk_bf16_f32 v58, v68, v69
	v_cvt_pk_bf16_f32 v59, v66, v67
	global_store_dwordx4 v[70:71], v[56:59], off
	s_nop 1
	v_mul_f32_e32 v56, v61, v61
	v_mul_f32_e32 v57, v63, v63
	v_fmac_f32_e32 v56, v60, v60
	v_fmac_f32_e32 v57, v62, v62
	v_add_f32_e32 v56, v56, v57
	v_mul_f32_e32 v57, v69, v69
	v_fmac_f32_e32 v57, v68, v68
	v_add_f32_e32 v56, v57, v56
	v_mul_f32_e32 v57, v67, v67
	v_fmac_f32_e32 v57, v66, v66
	v_add_f32_e32 v66, v57, v56
	s_waitcnt vmcnt(15)
	v_mov_b32_e32 v56, v212
	v_mov_b32_e32 v57, v213
	v_mov_b32_e32 v58, v214
	v_mov_b32_e32 v59, v215
	v_lshlrev_b32_e32 v60, 16, v56
	v_and_b32_e32 v61, 0xffff0000, v56
	v_lshlrev_b32_e32 v56, 16, v57
	v_and_b32_e32 v57, 0xffff0000, v57
	v_lshlrev_b32_e32 v62, 16, v58
	v_and_b32_e32 v63, 0xffff0000, v58
	v_lshlrev_b32_e32 v58, 16, v59
	v_and_b32_e32 v59, 0xffff0000, v59
	v_pk_add_f32 v[54:55], v[54:55], v[56:57]
	v_pk_add_f32 v[52:53], v[52:53], v[60:61]
	v_pk_add_f32 v[56:57], v[50:51], v[58:59]
	v_pk_add_f32 v[58:59], v[48:49], v[62:63]
	v_cvt_pk_bf16_f32 v48, v52, v53
	v_cvt_pk_bf16_f32 v49, v54, v55
	v_cvt_pk_bf16_f32 v50, v58, v59
	v_cvt_pk_bf16_f32 v51, v56, v57
	global_store_dwordx4 v[70:71], v[48:51], off offset:256
	s_nop 1
	v_mul_f32_e32 v48, v53, v53
	v_mul_f32_e32 v49, v55, v55
	v_fmac_f32_e32 v48, v52, v52
	v_fmac_f32_e32 v49, v54, v54
	v_add_f32_e32 v48, v48, v49
	v_mul_f32_e32 v49, v59, v59
	v_fmac_f32_e32 v49, v58, v58
	v_add_f32_e32 v48, v49, v48
	v_mul_f32_e32 v49, v57, v57
	v_fmac_f32_e32 v49, v56, v56
	v_add_f32_e32 v48, v49, v48
	v_add_f32_e32 v48, v66, v48
	ds_bpermute_b32 v49, v151, v48
	s_waitcnt lgkmcnt(0)
	v_add_f32_e32 v48, v48, v49
	ds_bpermute_b32 v49, v152, v48
	s_and_saveexec_b64 s[8:9], s[44:45]
	s_cbranch_execz .LBB0_679
	v_lshlrev_b64 v[50:51], 6, v[64:65]
	v_lshl_add_u64 v[50:51], s[0:1], 0, v[50:51]
	v_lshl_add_u64 v[50:51], s[36:37], 2, v[50:51]
	s_lshl_b32 s6, s18, 2
	v_lshl_add_u64 v[50:51], v[50:51], 0, s[6:7]
	s_waitcnt lgkmcnt(0)
	v_add_f32_e32 v48, v48, v49
	global_store_dword v[50:51], v48, off
.LBB0_679:
	s_or_b64 exec, exec, s[8:9]
	v_add_u32_e32 v48, 0x90, v146
	s_waitcnt lgkmcnt(0)
	v_ashrrev_i32_e32 v49, 31, v48
	v_lshlrev_b64 v[50:51], 11, v[48:49]
	v_lshl_add_u64 v[50:51], s[34:35], 0, v[50:51]
	v_lshl_add_u64 v[54:55], v[144:145], 1, v[50:51]
	s_waitcnt vmcnt(15)
	v_mov_b32_e32 v50, v216
	v_mov_b32_e32 v51, v217
	v_mov_b32_e32 v52, v218
	v_mov_b32_e32 v53, v219
	v_lshlrev_b32_e32 v56, 16, v50
	v_and_b32_e32 v57, 0xffff0000, v50
	v_lshlrev_b32_e32 v50, 16, v51
	v_and_b32_e32 v51, 0xffff0000, v51
	v_lshlrev_b32_e32 v58, 16, v52
	v_and_b32_e32 v59, 0xffff0000, v52
	v_lshlrev_b32_e32 v52, 16, v53
	v_and_b32_e32 v53, 0xffff0000, v53
	v_pk_add_f32 v[46:47], v[46:47], v[50:51]
	v_pk_add_f32 v[44:45], v[44:45], v[56:57]
	v_pk_add_f32 v[50:51], v[42:43], v[52:53]
	v_pk_add_f32 v[52:53], v[40:41], v[58:59]
	v_cvt_pk_bf16_f32 v40, v44, v45
	v_cvt_pk_bf16_f32 v41, v46, v47
	v_cvt_pk_bf16_f32 v42, v52, v53
	v_cvt_pk_bf16_f32 v43, v50, v51
	global_store_dwordx4 v[54:55], v[40:43], off
	s_nop 1
	v_mul_f32_e32 v40, v45, v45
	v_mul_f32_e32 v41, v47, v47
	v_fmac_f32_e32 v40, v44, v44
	v_fmac_f32_e32 v41, v46, v46
	v_add_f32_e32 v40, v40, v41
	v_mul_f32_e32 v41, v53, v53
	v_fmac_f32_e32 v41, v52, v52
	v_add_f32_e32 v40, v41, v40
	v_mul_f32_e32 v41, v51, v51
	v_fmac_f32_e32 v41, v50, v50
	v_add_f32_e32 v50, v41, v40
	s_waitcnt vmcnt(15)
	v_mov_b32_e32 v40, v220
	v_mov_b32_e32 v41, v221
	v_mov_b32_e32 v42, v222
	v_mov_b32_e32 v43, v223
	v_lshlrev_b32_e32 v44, 16, v40
	v_and_b32_e32 v45, 0xffff0000, v40
	v_lshlrev_b32_e32 v40, 16, v41
	v_and_b32_e32 v41, 0xffff0000, v41
	v_lshlrev_b32_e32 v46, 16, v42
	v_and_b32_e32 v47, 0xffff0000, v42
	v_lshlrev_b32_e32 v42, 16, v43
	v_and_b32_e32 v43, 0xffff0000, v43
	v_pk_add_f32 v[38:39], v[38:39], v[40:41]
	v_pk_add_f32 v[36:37], v[36:37], v[44:45]
	v_pk_add_f32 v[40:41], v[34:35], v[42:43]
	v_pk_add_f32 v[42:43], v[32:33], v[46:47]
	v_cvt_pk_bf16_f32 v32, v36, v37
	v_cvt_pk_bf16_f32 v33, v38, v39
	v_cvt_pk_bf16_f32 v34, v42, v43
	v_cvt_pk_bf16_f32 v35, v40, v41
	global_store_dwordx4 v[54:55], v[32:35], off offset:256
	s_nop 1
	v_mul_f32_e32 v32, v37, v37
	v_mul_f32_e32 v33, v39, v39
	v_fmac_f32_e32 v32, v36, v36
	v_fmac_f32_e32 v33, v38, v38
	v_add_f32_e32 v32, v32, v33
	v_mul_f32_e32 v33, v43, v43
	v_fmac_f32_e32 v33, v42, v42
	v_add_f32_e32 v32, v33, v32
	v_mul_f32_e32 v33, v41, v41
	v_fmac_f32_e32 v33, v40, v40
	v_add_f32_e32 v32, v33, v32
	v_add_f32_e32 v32, v50, v32
	ds_bpermute_b32 v33, v151, v32
	s_waitcnt lgkmcnt(0)
	v_add_f32_e32 v32, v32, v33
	ds_bpermute_b32 v33, v152, v32
	s_and_saveexec_b64 s[8:9], s[44:45]
	s_cbranch_execz .LBB0_681
	v_lshlrev_b64 v[34:35], 6, v[48:49]
	v_lshl_add_u64 v[34:35], s[0:1], 0, v[34:35]
	v_lshl_add_u64 v[34:35], s[36:37], 2, v[34:35]
	s_lshl_b32 s6, s18, 2
	v_lshl_add_u64 v[34:35], v[34:35], 0, s[6:7]
	s_waitcnt lgkmcnt(0)
	v_add_f32_e32 v32, v32, v33
	global_store_dword v[34:35], v32, off
.LBB0_681:
	s_or_b64 exec, exec, s[8:9]
	v_add_u32_e32 v32, 0xa0, v146
	s_waitcnt lgkmcnt(0)
	v_ashrrev_i32_e32 v33, 31, v32
	v_lshlrev_b64 v[34:35], 11, v[32:33]
	v_lshl_add_u64 v[34:35], s[34:35], 0, v[34:35]
	v_lshl_add_u64 v[38:39], v[144:145], 1, v[34:35]
	s_waitcnt vmcnt(15)
	v_mov_b32_e32 v34, v224
	v_mov_b32_e32 v35, v225
	v_mov_b32_e32 v36, v226
	v_mov_b32_e32 v37, v227
	v_lshlrev_b32_e32 v40, 16, v34
	v_and_b32_e32 v41, 0xffff0000, v34
	v_lshlrev_b32_e32 v34, 16, v35
	v_and_b32_e32 v35, 0xffff0000, v35
	v_lshlrev_b32_e32 v42, 16, v36
	v_and_b32_e32 v43, 0xffff0000, v36
	v_lshlrev_b32_e32 v36, 16, v37
	v_and_b32_e32 v37, 0xffff0000, v37
	v_pk_add_f32 v[30:31], v[30:31], v[34:35]
	v_pk_add_f32 v[28:29], v[28:29], v[40:41]
	v_pk_add_f32 v[34:35], v[26:27], v[36:37]
	v_pk_add_f32 v[36:37], v[24:25], v[42:43]
	v_cvt_pk_bf16_f32 v24, v28, v29
	v_cvt_pk_bf16_f32 v25, v30, v31
	v_cvt_pk_bf16_f32 v26, v36, v37
	v_cvt_pk_bf16_f32 v27, v34, v35
	global_store_dwordx4 v[38:39], v[24:27], off
	s_nop 1
	v_mul_f32_e32 v24, v29, v29
	v_mul_f32_e32 v25, v31, v31
	v_fmac_f32_e32 v24, v28, v28
	v_fmac_f32_e32 v25, v30, v30
	v_add_f32_e32 v24, v24, v25
	v_mul_f32_e32 v25, v37, v37
	v_fmac_f32_e32 v25, v36, v36
	v_add_f32_e32 v24, v25, v24
	v_mul_f32_e32 v25, v35, v35
	v_fmac_f32_e32 v25, v34, v34
	v_add_f32_e32 v34, v25, v24
	s_waitcnt vmcnt(15)
	v_mov_b32_e32 v24, v228
	v_mov_b32_e32 v25, v229
	v_mov_b32_e32 v26, v230
	v_mov_b32_e32 v27, v231
	v_lshlrev_b32_e32 v28, 16, v24
	v_and_b32_e32 v29, 0xffff0000, v24
	v_lshlrev_b32_e32 v24, 16, v25
	v_and_b32_e32 v25, 0xffff0000, v25
	v_lshlrev_b32_e32 v30, 16, v26
	v_and_b32_e32 v31, 0xffff0000, v26
	v_lshlrev_b32_e32 v26, 16, v27
	v_and_b32_e32 v27, 0xffff0000, v27
	v_pk_add_f32 v[22:23], v[22:23], v[24:25]
	v_pk_add_f32 v[20:21], v[20:21], v[28:29]
	v_pk_add_f32 v[24:25], v[18:19], v[26:27]
	v_pk_add_f32 v[26:27], v[16:17], v[30:31]
	v_cvt_pk_bf16_f32 v16, v20, v21
	v_cvt_pk_bf16_f32 v17, v22, v23
	v_cvt_pk_bf16_f32 v18, v26, v27
	v_cvt_pk_bf16_f32 v19, v24, v25
	global_store_dwordx4 v[38:39], v[16:19], off offset:256
	s_nop 1
	v_mul_f32_e32 v16, v21, v21
	v_mul_f32_e32 v17, v23, v23
	v_fmac_f32_e32 v16, v20, v20
	v_fmac_f32_e32 v17, v22, v22
	v_add_f32_e32 v16, v16, v17
	v_mul_f32_e32 v17, v27, v27
	v_fmac_f32_e32 v17, v26, v26
	v_add_f32_e32 v16, v17, v16
	v_mul_f32_e32 v17, v25, v25
	v_fmac_f32_e32 v17, v24, v24
	v_add_f32_e32 v16, v17, v16
	v_add_f32_e32 v16, v34, v16
	ds_bpermute_b32 v17, v151, v16
	s_waitcnt lgkmcnt(0)
	v_add_f32_e32 v16, v16, v17
	ds_bpermute_b32 v17, v152, v16
	s_and_saveexec_b64 s[8:9], s[44:45]
	s_cbranch_execz .LBB0_683
	v_lshlrev_b64 v[18:19], 6, v[32:33]
	v_lshl_add_u64 v[18:19], s[0:1], 0, v[18:19]
	v_lshl_add_u64 v[18:19], s[36:37], 2, v[18:19]
	s_lshl_b32 s6, s18, 2
	v_lshl_add_u64 v[18:19], v[18:19], 0, s[6:7]
	s_waitcnt lgkmcnt(0)
	v_add_f32_e32 v16, v16, v17
	global_store_dword v[18:19], v16, off
.LBB0_683:
	s_or_b64 exec, exec, s[8:9]
	v_add_u32_e32 v16, 0xb0, v146
	s_waitcnt lgkmcnt(0)
	v_ashrrev_i32_e32 v17, 31, v16
	v_lshlrev_b64 v[18:19], 11, v[16:17]
	v_lshl_add_u64 v[18:19], s[34:35], 0, v[18:19]
	v_lshl_add_u64 v[22:23], v[144:145], 1, v[18:19]
	s_waitcnt vmcnt(15)
	v_mov_b32_e32 v18, v232
	v_mov_b32_e32 v19, v233
	v_mov_b32_e32 v20, v234
	v_mov_b32_e32 v21, v235
	v_lshlrev_b32_e32 v24, 16, v18
	v_and_b32_e32 v25, 0xffff0000, v18
	v_lshlrev_b32_e32 v18, 16, v19
	v_and_b32_e32 v19, 0xffff0000, v19
	v_lshlrev_b32_e32 v26, 16, v20
	v_and_b32_e32 v27, 0xffff0000, v20
	v_lshlrev_b32_e32 v20, 16, v21
	v_and_b32_e32 v21, 0xffff0000, v21
	v_pk_add_f32 v[14:15], v[14:15], v[18:19]
	v_pk_add_f32 v[12:13], v[12:13], v[24:25]
	v_pk_add_f32 v[18:19], v[10:11], v[20:21]
	v_pk_add_f32 v[20:21], v[8:9], v[26:27]
	v_cvt_pk_bf16_f32 v8, v12, v13
	v_cvt_pk_bf16_f32 v9, v14, v15
	v_cvt_pk_bf16_f32 v10, v20, v21
	v_cvt_pk_bf16_f32 v11, v18, v19
	global_store_dwordx4 v[22:23], v[8:11], off
	s_nop 1
	v_mul_f32_e32 v8, v13, v13
	v_mul_f32_e32 v9, v15, v15
	v_fmac_f32_e32 v8, v12, v12
	v_fmac_f32_e32 v9, v14, v14
	v_add_f32_e32 v8, v8, v9
	v_mul_f32_e32 v9, v21, v21
	v_fmac_f32_e32 v9, v20, v20
	v_add_f32_e32 v8, v9, v8
	v_mul_f32_e32 v9, v19, v19
	v_fmac_f32_e32 v9, v18, v18
	v_add_f32_e32 v18, v9, v8
	s_waitcnt vmcnt(15)
	v_mov_b32_e32 v8, v236
	v_mov_b32_e32 v9, v237
	v_mov_b32_e32 v10, v238
	v_mov_b32_e32 v11, v239
	v_lshlrev_b32_e32 v12, 16, v8
	v_and_b32_e32 v13, 0xffff0000, v8
	v_lshlrev_b32_e32 v8, 16, v9
	v_and_b32_e32 v9, 0xffff0000, v9
	v_lshlrev_b32_e32 v14, 16, v10
	v_and_b32_e32 v15, 0xffff0000, v10
	v_lshlrev_b32_e32 v10, 16, v11
	v_and_b32_e32 v11, 0xffff0000, v11
	v_pk_add_f32 v[6:7], v[6:7], v[8:9]
	v_pk_add_f32 v[4:5], v[4:5], v[12:13]
	v_pk_add_f32 v[8:9], v[2:3], v[10:11]
	v_pk_add_f32 v[10:11], v[0:1], v[14:15]
	v_cvt_pk_bf16_f32 v0, v4, v5
	v_cvt_pk_bf16_f32 v1, v6, v7
	v_cvt_pk_bf16_f32 v2, v10, v11
	v_cvt_pk_bf16_f32 v3, v8, v9
	global_store_dwordx4 v[22:23], v[0:3], off offset:256
	s_nop 1
	v_mul_f32_e32 v0, v5, v5
	v_mul_f32_e32 v1, v7, v7
	v_fmac_f32_e32 v0, v4, v4
	v_fmac_f32_e32 v1, v6, v6
	v_add_f32_e32 v0, v0, v1
	v_mul_f32_e32 v1, v11, v11
	v_fmac_f32_e32 v1, v10, v10
	v_add_f32_e32 v0, v1, v0
	v_mul_f32_e32 v1, v9, v9
	v_fmac_f32_e32 v1, v8, v8
	v_add_f32_e32 v0, v1, v0
	v_add_f32_e32 v0, v18, v0
	ds_bpermute_b32 v1, v151, v0
	s_waitcnt lgkmcnt(0)
	v_add_f32_e32 v0, v0, v1
	ds_bpermute_b32 v1, v152, v0
	s_and_saveexec_b64 s[8:9], s[44:45]
	s_cbranch_execz .LBB0_685
	v_lshlrev_b64 v[2:3], 6, v[16:17]
	v_lshl_add_u64 v[2:3], s[0:1], 0, v[2:3]
	v_lshl_add_u64 v[2:3], s[36:37], 2, v[2:3]
	s_lshl_b32 s6, s18, 2
	v_lshl_add_u64 v[2:3], v[2:3], 0, s[6:7]
	s_waitcnt lgkmcnt(0)
	v_add_f32_e32 v0, v0, v1
	global_store_dword v[2:3], v0, off

.LBB0_844:
	v_lshl_add_u32 v146, s30, 8, v148
	v_ashrrev_i32_e32 v147, 31, v146
	v_lshl_add_u32 v144, s6, 8, v150
	v_lshlrev_b64 v[156:157], 11, v[146:147]
	v_ashrrev_i32_e32 v145, 31, v144
	v_lshl_add_u32 v174, v144, 1, v156
	global_load_dwordx4 v[170:173], v174, s[34:35]
	s_nop 0
	global_load_dwordx4 v[174:177], v174, s[34:35] offset:256
	v_lshl_add_u32 v182, v144, 1, v156
	v_add_u32_e32 v182, 0x8000, v182
	global_load_dwordx4 v[178:181], v182, s[34:35]
	s_nop 0
	global_load_dwordx4 v[182:185], v182, s[34:35] offset:256
	v_lshl_add_u32 v190, v144, 1, v156
	v_add_u32_e32 v190, 0x10000, v190
	global_load_dwordx4 v[186:189], v190, s[34:35]
	s_nop 0
	global_load_dwordx4 v[190:193], v190, s[34:35] offset:256
	v_lshl_add_u32 v204, v144, 1, v156
	v_add_u32_e32 v204, 0x18000, v204
	global_load_dwordx4 v[200:203], v204, s[34:35]
	s_nop 0
	global_load_dwordx4 v[204:207], v204, s[34:35] offset:256
	v_lshl_add_u32 v212, v144, 1, v156
	v_add_u32_e32 v212, 0x40000, v212
	global_load_dwordx4 v[208:211], v212, s[34:35]
	s_nop 0
	global_load_dwordx4 v[212:215], v212, s[34:35] offset:256
	v_lshl_add_u32 v220, v144, 1, v156
	v_add_u32_e32 v220, 0x48000, v220
	global_load_dwordx4 v[216:219], v220, s[34:35]
	s_nop 0
	global_load_dwordx4 v[220:223], v220, s[34:35] offset:256
	v_lshl_add_u32 v228, v144, 1, v156
	v_add_u32_e32 v228, 0x50000, v228
	global_load_dwordx4 v[224:227], v228, s[34:35]
	s_nop 0
	global_load_dwordx4 v[228:231], v228, s[34:35] offset:256
	v_lshl_add_u32 v236, v144, 1, v156
	v_add_u32_e32 v236, 0x58000, v236
	global_load_dwordx4 v[232:235], v236, s[34:35]
	s_nop 0
	global_load_dwordx4 v[236:239], v236, s[34:35] offset:256
	v_lshl_add_u64 v[156:157], s[34:35], 0, v[156:157]
	v_lshl_add_u64 v[156:157], v[144:145], 1, v[156:157]
	s_lshl_b32 s30, s6, 2
	s_ashr_i32 s31, s30, 31
	s_waitcnt vmcnt(15)
	v_mov_b32_e32 v162, v170
	v_mov_b32_e32 v163, v171
	v_mov_b32_e32 v164, v172
	v_mov_b32_e32 v165, v173
	v_lshlrev_b32_e32 v166, 16, v162
	v_and_b32_e32 v167, 0xffff0000, v162
	v_lshlrev_b32_e32 v162, 16, v163
	v_and_b32_e32 v163, 0xffff0000, v163
	v_lshlrev_b32_e32 v168, 16, v164
	v_and_b32_e32 v169, 0xffff0000, v164
	v_lshlrev_b32_e32 v164, 16, v165
	v_and_b32_e32 v165, 0xffff0000, v165
	v_pk_add_f32 v[126:127], v[126:127], v[162:163]
	v_pk_add_f32 v[124:125], v[124:125], v[166:167]
	v_pk_add_f32 v[162:163], v[122:123], v[164:165]
	v_pk_add_f32 v[164:165], v[120:121], v[168:169]
	v_cvt_pk_bf16_f32 v120, v124, v125
	v_cvt_pk_bf16_f32 v121, v126, v127
	v_cvt_pk_bf16_f32 v122, v164, v165
	v_cvt_pk_bf16_f32 v123, v162, v163
	global_store_dwordx4 v[156:157], v[120:123], off
	s_nop 1
	v_mul_f32_e32 v120, v125, v125
	v_mul_f32_e32 v121, v127, v127
	v_fmac_f32_e32 v120, v124, v124
	v_fmac_f32_e32 v121, v126, v126
	v_add_f32_e32 v120, v120, v121
	v_mul_f32_e32 v121, v165, v165
	v_fmac_f32_e32 v121, v164, v164
	v_add_f32_e32 v120, v121, v120
	v_mul_f32_e32 v121, v163, v163
	v_fmac_f32_e32 v121, v162, v162
	v_add_f32_e32 v158, v121, v120
	s_waitcnt vmcnt(15)
	v_mov_b32_e32 v120, v174
	v_mov_b32_e32 v121, v175
	v_mov_b32_e32 v122, v176
	v_mov_b32_e32 v123, v177
	v_lshlrev_b32_e32 v124, 16, v120
	v_and_b32_e32 v125, 0xffff0000, v120
	v_lshlrev_b32_e32 v120, 16, v121
	v_and_b32_e32 v121, 0xffff0000, v121
	v_lshlrev_b32_e32 v126, 16, v122
	v_and_b32_e32 v127, 0xffff0000, v122
	v_lshlrev_b32_e32 v122, 16, v123
	v_and_b32_e32 v123, 0xffff0000, v123
	v_pk_add_f32 v[118:119], v[118:119], v[120:121]
	v_pk_add_f32 v[116:117], v[116:117], v[124:125]
	v_pk_add_f32 v[120:121], v[114:115], v[122:123]
	v_pk_add_f32 v[122:123], v[112:113], v[126:127]
	v_cvt_pk_bf16_f32 v112, v116, v117
	v_cvt_pk_bf16_f32 v113, v118, v119
	v_cvt_pk_bf16_f32 v114, v122, v123
	v_cvt_pk_bf16_f32 v115, v120, v121
	global_store_dwordx4 v[156:157], v[112:115], off offset:256
	s_nop 1
	v_mul_f32_e32 v112, v117, v117
	v_mul_f32_e32 v113, v119, v119
	v_fmac_f32_e32 v112, v116, v116
	v_fmac_f32_e32 v113, v118, v118
	v_add_f32_e32 v112, v112, v113
	v_mul_f32_e32 v113, v123, v123
	v_fmac_f32_e32 v113, v122, v122
	v_add_f32_e32 v112, v113, v112
	v_mul_f32_e32 v113, v121, v121
	v_fmac_f32_e32 v113, v120, v120
	v_add_f32_e32 v112, v113, v112
	v_add_f32_e32 v112, v158, v112
	ds_bpermute_b32 v113, v151, v112
	s_waitcnt lgkmcnt(0)
	v_add_f32_e32 v112, v112, v113
	ds_bpermute_b32 v113, v152, v112
	s_and_saveexec_b64 s[8:9], s[44:45]
	s_cbranch_execz .LBB0_846
	v_lshlrev_b64 v[114:115], 6, v[146:147]
	v_lshl_add_u64 v[114:115], s[0:1], 0, v[114:115]
	v_lshl_add_u64 v[114:115], s[30:31], 2, v[114:115]
	s_lshl_b32 s6, s33, 2
	v_lshl_add_u64 v[114:115], v[114:115], 0, s[6:7]
	s_waitcnt lgkmcnt(0)
	v_add_f32_e32 v112, v112, v113
	global_store_dword v[114:115], v112, off
.LBB0_846:
	s_or_b64 exec, exec, s[8:9]
	v_or_b32_e32 v112, 16, v146
	s_waitcnt lgkmcnt(0)
	v_ashrrev_i32_e32 v113, 31, v112
	v_lshlrev_b64 v[114:115], 11, v[112:113]
	v_lshl_add_u64 v[114:115], s[34:35], 0, v[114:115]
	v_lshl_add_u64 v[118:119], v[144:145], 1, v[114:115]
	s_waitcnt vmcnt(15)
	v_mov_b32_e32 v114, v178
	v_mov_b32_e32 v115, v179
	v_mov_b32_e32 v116, v180
	v_mov_b32_e32 v117, v181
	v_lshlrev_b32_e32 v120, 16, v114
	v_and_b32_e32 v121, 0xffff0000, v114
	v_lshlrev_b32_e32 v114, 16, v115
	v_and_b32_e32 v115, 0xffff0000, v115
	v_lshlrev_b32_e32 v122, 16, v116
	v_and_b32_e32 v123, 0xffff0000, v116
	v_lshlrev_b32_e32 v116, 16, v117
	v_and_b32_e32 v117, 0xffff0000, v117
	v_pk_add_f32 v[110:111], v[110:111], v[114:115]
	v_pk_add_f32 v[108:109], v[108:109], v[120:121]
	v_pk_add_f32 v[114:115], v[106:107], v[116:117]
	v_pk_add_f32 v[116:117], v[104:105], v[122:123]
	v_cvt_pk_bf16_f32 v104, v108, v109
	v_cvt_pk_bf16_f32 v105, v110, v111
	v_cvt_pk_bf16_f32 v106, v116, v117
	v_cvt_pk_bf16_f32 v107, v114, v115
	global_store_dwordx4 v[118:119], v[104:107], off
	s_nop 1
	v_mul_f32_e32 v104, v109, v109
	v_mul_f32_e32 v105, v111, v111
	v_fmac_f32_e32 v104, v108, v108
	v_fmac_f32_e32 v105, v110, v110
	v_add_f32_e32 v104, v104, v105
	v_mul_f32_e32 v105, v117, v117
	v_fmac_f32_e32 v105, v116, v116
	v_add_f32_e32 v104, v105, v104
	v_mul_f32_e32 v105, v115, v115
	v_fmac_f32_e32 v105, v114, v114
	v_add_f32_e32 v114, v105, v104
	s_waitcnt vmcnt(15)
	v_mov_b32_e32 v104, v182
	v_mov_b32_e32 v105, v183
	v_mov_b32_e32 v106, v184
	v_mov_b32_e32 v107, v185
	v_lshlrev_b32_e32 v108, 16, v104
	v_and_b32_e32 v109, 0xffff0000, v104
	v_lshlrev_b32_e32 v104, 16, v105
	v_and_b32_e32 v105, 0xffff0000, v105
	v_lshlrev_b32_e32 v110, 16, v106
	v_and_b32_e32 v111, 0xffff0000, v106
	v_lshlrev_b32_e32 v106, 16, v107
	v_and_b32_e32 v107, 0xffff0000, v107
	v_pk_add_f32 v[102:103], v[102:103], v[104:105]
	v_pk_add_f32 v[100:101], v[100:101], v[108:109]
	v_pk_add_f32 v[104:105], v[98:99], v[106:107]
	v_pk_add_f32 v[106:107], v[96:97], v[110:111]
	v_cvt_pk_bf16_f32 v96, v100, v101
	v_cvt_pk_bf16_f32 v97, v102, v103
	v_cvt_pk_bf16_f32 v98, v106, v107
	v_cvt_pk_bf16_f32 v99, v104, v105
	global_store_dwordx4 v[118:119], v[96:99], off offset:256
	s_nop 1
	v_mul_f32_e32 v96, v101, v101
	v_mul_f32_e32 v97, v103, v103
	v_fmac_f32_e32 v96, v100, v100
	v_fmac_f32_e32 v97, v102, v102
	v_add_f32_e32 v96, v96, v97
	v_mul_f32_e32 v97, v107, v107
	v_fmac_f32_e32 v97, v106, v106
	v_add_f32_e32 v96, v97, v96
	v_mul_f32_e32 v97, v105, v105
	v_fmac_f32_e32 v97, v104, v104
	v_add_f32_e32 v96, v97, v96
	v_add_f32_e32 v96, v114, v96
	ds_bpermute_b32 v97, v151, v96
	s_waitcnt lgkmcnt(0)
	v_add_f32_e32 v96, v96, v97
	ds_bpermute_b32 v97, v152, v96
	s_and_saveexec_b64 s[8:9], s[44:45]
	s_cbranch_execz .LBB0_848
	v_lshlrev_b64 v[98:99], 6, v[112:113]
	v_lshl_add_u64 v[98:99], s[0:1], 0, v[98:99]
	v_lshl_add_u64 v[98:99], s[30:31], 2, v[98:99]
	s_lshl_b32 s6, s33, 2
	v_lshl_add_u64 v[98:99], v[98:99], 0, s[6:7]
	s_waitcnt lgkmcnt(0)
	v_add_f32_e32 v96, v96, v97
	global_store_dword v[98:99], v96, off
.LBB0_848:
	s_or_b64 exec, exec, s[8:9]
	v_or_b32_e32 v96, 32, v146
	s_waitcnt lgkmcnt(0)
	v_ashrrev_i32_e32 v97, 31, v96
	v_lshlrev_b64 v[98:99], 11, v[96:97]
	v_lshl_add_u64 v[98:99], s[34:35], 0, v[98:99]
	v_lshl_add_u64 v[102:103], v[144:145], 1, v[98:99]
	s_waitcnt vmcnt(15)
	v_mov_b32_e32 v98, v186
	v_mov_b32_e32 v99, v187
	v_mov_b32_e32 v100, v188
	v_mov_b32_e32 v101, v189
	v_lshlrev_b32_e32 v104, 16, v98
	v_and_b32_e32 v105, 0xffff0000, v98
	v_lshlrev_b32_e32 v98, 16, v99
	v_and_b32_e32 v99, 0xffff0000, v99
	v_lshlrev_b32_e32 v106, 16, v100
	v_and_b32_e32 v107, 0xffff0000, v100
	v_lshlrev_b32_e32 v100, 16, v101
	v_and_b32_e32 v101, 0xffff0000, v101
	v_pk_add_f32 v[94:95], v[94:95], v[98:99]
	v_pk_add_f32 v[92:93], v[92:93], v[104:105]
	v_pk_add_f32 v[98:99], v[90:91], v[100:101]
	v_pk_add_f32 v[100:101], v[88:89], v[106:107]
	v_cvt_pk_bf16_f32 v88, v92, v93
	v_cvt_pk_bf16_f32 v89, v94, v95
	v_cvt_pk_bf16_f32 v90, v100, v101
	v_cvt_pk_bf16_f32 v91, v98, v99
	global_store_dwordx4 v[102:103], v[88:91], off
	s_nop 1
	v_mul_f32_e32 v88, v93, v93
	v_mul_f32_e32 v89, v95, v95
	v_fmac_f32_e32 v88, v92, v92
	v_fmac_f32_e32 v89, v94, v94
	v_add_f32_e32 v88, v88, v89
	v_mul_f32_e32 v89, v101, v101
	v_fmac_f32_e32 v89, v100, v100
	v_add_f32_e32 v88, v89, v88
	v_mul_f32_e32 v89, v99, v99
	v_fmac_f32_e32 v89, v98, v98
	v_add_f32_e32 v98, v89, v88
	s_waitcnt vmcnt(15)
	v_mov_b32_e32 v88, v190
	v_mov_b32_e32 v89, v191
	v_mov_b32_e32 v90, v192
	v_mov_b32_e32 v91, v193
	v_lshlrev_b32_e32 v92, 16, v88
	v_and_b32_e32 v93, 0xffff0000, v88
	v_lshlrev_b32_e32 v88, 16, v89
	v_and_b32_e32 v89, 0xffff0000, v89
	v_lshlrev_b32_e32 v94, 16, v90
	v_and_b32_e32 v95, 0xffff0000, v90
	v_lshlrev_b32_e32 v90, 16, v91
	v_and_b32_e32 v91, 0xffff0000, v91
	v_pk_add_f32 v[86:87], v[86:87], v[88:89]
	v_pk_add_f32 v[84:85], v[84:85], v[92:93]
	v_pk_add_f32 v[88:89], v[82:83], v[90:91]
	v_pk_add_f32 v[90:91], v[80:81], v[94:95]
	v_cvt_pk_bf16_f32 v80, v84, v85
	v_cvt_pk_bf16_f32 v81, v86, v87
	v_cvt_pk_bf16_f32 v82, v90, v91
	v_cvt_pk_bf16_f32 v83, v88, v89
	global_store_dwordx4 v[102:103], v[80:83], off offset:256
	s_nop 1
	v_mul_f32_e32 v80, v85, v85
	v_mul_f32_e32 v81, v87, v87
	v_fmac_f32_e32 v80, v84, v84
	v_fmac_f32_e32 v81, v86, v86
	v_add_f32_e32 v80, v80, v81
	v_mul_f32_e32 v81, v91, v91
	v_fmac_f32_e32 v81, v90, v90
	v_add_f32_e32 v80, v81, v80
	v_mul_f32_e32 v81, v89, v89
	v_fmac_f32_e32 v81, v88, v88
	v_add_f32_e32 v80, v81, v80
	v_add_f32_e32 v80, v98, v80
	ds_bpermute_b32 v81, v151, v80
	s_waitcnt lgkmcnt(0)
	v_add_f32_e32 v80, v80, v81
	ds_bpermute_b32 v81, v152, v80
	s_and_saveexec_b64 s[8:9], s[44:45]
	s_cbranch_execz .LBB0_850
	v_lshlrev_b64 v[82:83], 6, v[96:97]
	v_lshl_add_u64 v[82:83], s[0:1], 0, v[82:83]
	v_lshl_add_u64 v[82:83], s[30:31], 2, v[82:83]
	s_lshl_b32 s6, s33, 2
	v_lshl_add_u64 v[82:83], v[82:83], 0, s[6:7]
	s_waitcnt lgkmcnt(0)
	v_add_f32_e32 v80, v80, v81
	global_store_dword v[82:83], v80, off
.LBB0_850:
	s_or_b64 exec, exec, s[8:9]
	v_or_b32_e32 v80, 48, v146
	s_waitcnt lgkmcnt(0)
	v_ashrrev_i32_e32 v81, 31, v80
	v_lshlrev_b64 v[82:83], 11, v[80:81]
	v_lshl_add_u64 v[82:83], s[34:35], 0, v[82:83]
	v_lshl_add_u64 v[86:87], v[144:145], 1, v[82:83]
	s_waitcnt vmcnt(15)
	v_mov_b32_e32 v82, v200
	v_mov_b32_e32 v83, v201
	v_mov_b32_e32 v84, v202
	v_mov_b32_e32 v85, v203
	v_lshlrev_b32_e32 v88, 16, v82
	v_and_b32_e32 v89, 0xffff0000, v82
	v_lshlrev_b32_e32 v82, 16, v83
	v_and_b32_e32 v83, 0xffff0000, v83
	v_lshlrev_b32_e32 v90, 16, v84
	v_and_b32_e32 v91, 0xffff0000, v84
	v_lshlrev_b32_e32 v84, 16, v85
	v_and_b32_e32 v85, 0xffff0000, v85
	v_pk_add_f32 v[78:79], v[78:79], v[82:83]
	v_pk_add_f32 v[76:77], v[76:77], v[88:89]
	v_pk_add_f32 v[82:83], v[74:75], v[84:85]
	v_pk_add_f32 v[84:85], v[72:73], v[90:91]
	v_cvt_pk_bf16_f32 v72, v76, v77
	v_cvt_pk_bf16_f32 v73, v78, v79
	v_cvt_pk_bf16_f32 v74, v84, v85
	v_cvt_pk_bf16_f32 v75, v82, v83
	global_store_dwordx4 v[86:87], v[72:75], off
	s_nop 1
	v_mul_f32_e32 v72, v77, v77
	v_mul_f32_e32 v73, v79, v79
	v_fmac_f32_e32 v72, v76, v76
	v_fmac_f32_e32 v73, v78, v78
	v_add_f32_e32 v72, v72, v73
	v_mul_f32_e32 v73, v85, v85
	v_fmac_f32_e32 v73, v84, v84
	v_add_f32_e32 v72, v73, v72
	v_mul_f32_e32 v73, v83, v83
	v_fmac_f32_e32 v73, v82, v82
	v_add_f32_e32 v82, v73, v72
	s_waitcnt vmcnt(15)
	v_mov_b32_e32 v72, v204
	v_mov_b32_e32 v73, v205
	v_mov_b32_e32 v74, v206
	v_mov_b32_e32 v75, v207
	v_lshlrev_b32_e32 v76, 16, v72
	v_and_b32_e32 v77, 0xffff0000, v72
	v_lshlrev_b32_e32 v72, 16, v73
	v_and_b32_e32 v73, 0xffff0000, v73
	v_lshlrev_b32_e32 v78, 16, v74
	v_and_b32_e32 v79, 0xffff0000, v74
	v_lshlrev_b32_e32 v74, 16, v75
	v_and_b32_e32 v75, 0xffff0000, v75
	v_pk_add_f32 v[70:71], v[70:71], v[72:73]
	v_pk_add_f32 v[68:69], v[68:69], v[76:77]
	v_pk_add_f32 v[72:73], v[66:67], v[74:75]
	v_pk_add_f32 v[74:75], v[64:65], v[78:79]
	v_cvt_pk_bf16_f32 v64, v68, v69
	v_cvt_pk_bf16_f32 v65, v70, v71
	v_cvt_pk_bf16_f32 v66, v74, v75
	v_cvt_pk_bf16_f32 v67, v72, v73
	global_store_dwordx4 v[86:87], v[64:67], off offset:256
	s_nop 1
	v_mul_f32_e32 v64, v69, v69
	v_mul_f32_e32 v65, v71, v71
	v_fmac_f32_e32 v64, v68, v68
	v_fmac_f32_e32 v65, v70, v70
	v_add_f32_e32 v64, v64, v65
	v_mul_f32_e32 v65, v75, v75
	v_fmac_f32_e32 v65, v74, v74
	v_add_f32_e32 v64, v65, v64
	v_mul_f32_e32 v65, v73, v73
	v_fmac_f32_e32 v65, v72, v72
	v_add_f32_e32 v64, v65, v64
	v_add_f32_e32 v64, v82, v64
	ds_bpermute_b32 v65, v151, v64
	s_waitcnt lgkmcnt(0)
	v_add_f32_e32 v64, v64, v65
	ds_bpermute_b32 v65, v152, v64
	s_and_saveexec_b64 s[8:9], s[44:45]
	s_cbranch_execz .LBB0_852
	v_lshlrev_b64 v[66:67], 6, v[80:81]
	v_lshl_add_u64 v[66:67], s[0:1], 0, v[66:67]
	v_lshl_add_u64 v[66:67], s[30:31], 2, v[66:67]
	s_lshl_b32 s6, s33, 2
	v_lshl_add_u64 v[66:67], v[66:67], 0, s[6:7]
	s_waitcnt lgkmcnt(0)
	v_add_f32_e32 v64, v64, v65
	global_store_dword v[66:67], v64, off
.LBB0_852:
	s_or_b64 exec, exec, s[8:9]
	v_add_u32_e32 v64, 0x80, v146
	s_waitcnt lgkmcnt(0)
	v_ashrrev_i32_e32 v65, 31, v64
	v_lshlrev_b64 v[66:67], 11, v[64:65]
	v_lshl_add_u64 v[66:67], s[34:35], 0, v[66:67]
	v_lshl_add_u64 v[70:71], v[144:145], 1, v[66:67]
	s_waitcnt vmcnt(15)
	v_mov_b32_e32 v66, v208
	v_mov_b32_e32 v67, v209
	v_mov_b32_e32 v68, v210
	v_mov_b32_e32 v69, v211
	v_lshlrev_b32_e32 v72, 16, v66
	v_and_b32_e32 v73, 0xffff0000, v66
	v_lshlrev_b32_e32 v66, 16, v67
	v_and_b32_e32 v67, 0xffff0000, v67
	v_lshlrev_b32_e32 v74, 16, v68
	v_and_b32_e32 v75, 0xffff0000, v68
	v_lshlrev_b32_e32 v68, 16, v69
	v_and_b32_e32 v69, 0xffff0000, v69
	v_pk_add_f32 v[62:63], v[62:63], v[66:67]
	v_pk_add_f32 v[60:61], v[60:61], v[72:73]
	v_pk_add_f32 v[66:67], v[58:59], v[68:69]
	v_pk_add_f32 v[68:69], v[56:57], v[74:75]
	v_cvt_pk_bf16_f32 v56, v60, v61
	v_cvt_pk_bf16_f32 v57, v62, v63
	v_cvt_pk_bf16_f32 v58, v68, v69
	v_cvt_pk_bf16_f32 v59, v66, v67
	global_store_dwordx4 v[70:71], v[56:59], off
	s_nop 1
	v_mul_f32_e32 v56, v61, v61
	v_mul_f32_e32 v57, v63, v63
	v_fmac_f32_e32 v56, v60, v60
	v_fmac_f32_e32 v57, v62, v62
	v_add_f32_e32 v56, v56, v57
	v_mul_f32_e32 v57, v69, v69
	v_fmac_f32_e32 v57, v68, v68
	v_add_f32_e32 v56, v57, v56
	v_mul_f32_e32 v57, v67, v67
	v_fmac_f32_e32 v57, v66, v66
	v_add_f32_e32 v66, v57, v56
	s_waitcnt vmcnt(15)
	v_mov_b32_e32 v56, v212
	v_mov_b32_e32 v57, v213
	v_mov_b32_e32 v58, v214
	v_mov_b32_e32 v59, v215
	v_lshlrev_b32_e32 v60, 16, v56
	v_and_b32_e32 v61, 0xffff0000, v56
	v_lshlrev_b32_e32 v56, 16, v57
	v_and_b32_e32 v57, 0xffff0000, v57
	v_lshlrev_b32_e32 v62, 16, v58
	v_and_b32_e32 v63, 0xffff0000, v58
	v_lshlrev_b32_e32 v58, 16, v59
	v_and_b32_e32 v59, 0xffff0000, v59
	v_pk_add_f32 v[54:55], v[54:55], v[56:57]
	v_pk_add_f32 v[52:53], v[52:53], v[60:61]
	v_pk_add_f32 v[56:57], v[50:51], v[58:59]
	v_pk_add_f32 v[58:59], v[48:49], v[62:63]
	v_cvt_pk_bf16_f32 v48, v52, v53
	v_cvt_pk_bf16_f32 v49, v54, v55
	v_cvt_pk_bf16_f32 v50, v58, v59
	v_cvt_pk_bf16_f32 v51, v56, v57
	global_store_dwordx4 v[70:71], v[48:51], off offset:256
	s_nop 1
	v_mul_f32_e32 v48, v53, v53
	v_mul_f32_e32 v49, v55, v55
	v_fmac_f32_e32 v48, v52, v52
	v_fmac_f32_e32 v49, v54, v54
	v_add_f32_e32 v48, v48, v49
	v_mul_f32_e32 v49, v59, v59
	v_fmac_f32_e32 v49, v58, v58
	v_add_f32_e32 v48, v49, v48
	v_mul_f32_e32 v49, v57, v57
	v_fmac_f32_e32 v49, v56, v56
	v_add_f32_e32 v48, v49, v48
	v_add_f32_e32 v48, v66, v48
	ds_bpermute_b32 v49, v151, v48
	s_waitcnt lgkmcnt(0)
	v_add_f32_e32 v48, v48, v49
	ds_bpermute_b32 v49, v152, v48
	s_and_saveexec_b64 s[8:9], s[44:45]
	s_cbranch_execz .LBB0_854
	v_lshlrev_b64 v[50:51], 6, v[64:65]
	v_lshl_add_u64 v[50:51], s[0:1], 0, v[50:51]
	v_lshl_add_u64 v[50:51], s[30:31], 2, v[50:51]
	s_lshl_b32 s6, s33, 2
	v_lshl_add_u64 v[50:51], v[50:51], 0, s[6:7]
	s_waitcnt lgkmcnt(0)
	v_add_f32_e32 v48, v48, v49
	global_store_dword v[50:51], v48, off
.LBB0_854:
	s_or_b64 exec, exec, s[8:9]
	v_add_u32_e32 v48, 0x90, v146
	s_waitcnt lgkmcnt(0)
	v_ashrrev_i32_e32 v49, 31, v48
	v_lshlrev_b64 v[50:51], 11, v[48:49]
	v_lshl_add_u64 v[50:51], s[34:35], 0, v[50:51]
	v_lshl_add_u64 v[54:55], v[144:145], 1, v[50:51]
	s_waitcnt vmcnt(15)
	v_mov_b32_e32 v50, v216
	v_mov_b32_e32 v51, v217
	v_mov_b32_e32 v52, v218
	v_mov_b32_e32 v53, v219
	v_lshlrev_b32_e32 v56, 16, v50
	v_and_b32_e32 v57, 0xffff0000, v50
	v_lshlrev_b32_e32 v50, 16, v51
	v_and_b32_e32 v51, 0xffff0000, v51
	v_lshlrev_b32_e32 v58, 16, v52
	v_and_b32_e32 v59, 0xffff0000, v52
	v_lshlrev_b32_e32 v52, 16, v53
	v_and_b32_e32 v53, 0xffff0000, v53
	v_pk_add_f32 v[46:47], v[46:47], v[50:51]
	v_pk_add_f32 v[44:45], v[44:45], v[56:57]
	v_pk_add_f32 v[50:51], v[42:43], v[52:53]
	v_pk_add_f32 v[52:53], v[40:41], v[58:59]
	v_cvt_pk_bf16_f32 v40, v44, v45
	v_cvt_pk_bf16_f32 v41, v46, v47
	v_cvt_pk_bf16_f32 v42, v52, v53
	v_cvt_pk_bf16_f32 v43, v50, v51
	global_store_dwordx4 v[54:55], v[40:43], off
	s_nop 1
	v_mul_f32_e32 v40, v45, v45
	v_mul_f32_e32 v41, v47, v47
	v_fmac_f32_e32 v40, v44, v44
	v_fmac_f32_e32 v41, v46, v46
	v_add_f32_e32 v40, v40, v41
	v_mul_f32_e32 v41, v53, v53
	v_fmac_f32_e32 v41, v52, v52
	v_add_f32_e32 v40, v41, v40
	v_mul_f32_e32 v41, v51, v51
	v_fmac_f32_e32 v41, v50, v50
	v_add_f32_e32 v50, v41, v40
	s_waitcnt vmcnt(15)
	v_mov_b32_e32 v40, v220
	v_mov_b32_e32 v41, v221
	v_mov_b32_e32 v42, v222
	v_mov_b32_e32 v43, v223
	v_lshlrev_b32_e32 v44, 16, v40
	v_and_b32_e32 v45, 0xffff0000, v40
	v_lshlrev_b32_e32 v40, 16, v41
	v_and_b32_e32 v41, 0xffff0000, v41
	v_lshlrev_b32_e32 v46, 16, v42
	v_and_b32_e32 v47, 0xffff0000, v42
	v_lshlrev_b32_e32 v42, 16, v43
	v_and_b32_e32 v43, 0xffff0000, v43
	v_pk_add_f32 v[38:39], v[38:39], v[40:41]
	v_pk_add_f32 v[36:37], v[36:37], v[44:45]
	v_pk_add_f32 v[40:41], v[34:35], v[42:43]
	v_pk_add_f32 v[42:43], v[32:33], v[46:47]
	v_cvt_pk_bf16_f32 v32, v36, v37
	v_cvt_pk_bf16_f32 v33, v38, v39
	v_cvt_pk_bf16_f32 v34, v42, v43
	v_cvt_pk_bf16_f32 v35, v40, v41
	global_store_dwordx4 v[54:55], v[32:35], off offset:256
	s_nop 1
	v_mul_f32_e32 v32, v37, v37
	v_mul_f32_e32 v33, v39, v39
	v_fmac_f32_e32 v32, v36, v36
	v_fmac_f32_e32 v33, v38, v38
	v_add_f32_e32 v32, v32, v33
	v_mul_f32_e32 v33, v43, v43
	v_fmac_f32_e32 v33, v42, v42
	v_add_f32_e32 v32, v33, v32
	v_mul_f32_e32 v33, v41, v41
	v_fmac_f32_e32 v33, v40, v40
	v_add_f32_e32 v32, v33, v32
	v_add_f32_e32 v32, v50, v32
	ds_bpermute_b32 v33, v151, v32
	s_waitcnt lgkmcnt(0)
	v_add_f32_e32 v32, v32, v33
	ds_bpermute_b32 v33, v152, v32
	s_and_saveexec_b64 s[8:9], s[44:45]
	s_cbranch_execz .LBB0_856
	v_lshlrev_b64 v[34:35], 6, v[48:49]
	v_lshl_add_u64 v[34:35], s[0:1], 0, v[34:35]
	v_lshl_add_u64 v[34:35], s[30:31], 2, v[34:35]
	s_lshl_b32 s6, s33, 2
	v_lshl_add_u64 v[34:35], v[34:35], 0, s[6:7]
	s_waitcnt lgkmcnt(0)
	v_add_f32_e32 v32, v32, v33
	global_store_dword v[34:35], v32, off
.LBB0_856:
	s_or_b64 exec, exec, s[8:9]
	v_add_u32_e32 v32, 0xa0, v146
	s_waitcnt lgkmcnt(0)
	v_ashrrev_i32_e32 v33, 31, v32
	v_lshlrev_b64 v[34:35], 11, v[32:33]
	v_lshl_add_u64 v[34:35], s[34:35], 0, v[34:35]
	v_lshl_add_u64 v[38:39], v[144:145], 1, v[34:35]
	s_waitcnt vmcnt(15)
	v_mov_b32_e32 v34, v224
	v_mov_b32_e32 v35, v225
	v_mov_b32_e32 v36, v226
	v_mov_b32_e32 v37, v227
	v_lshlrev_b32_e32 v40, 16, v34
	v_and_b32_e32 v41, 0xffff0000, v34
	v_lshlrev_b32_e32 v34, 16, v35
	v_and_b32_e32 v35, 0xffff0000, v35
	v_lshlrev_b32_e32 v42, 16, v36
	v_and_b32_e32 v43, 0xffff0000, v36
	v_lshlrev_b32_e32 v36, 16, v37
	v_and_b32_e32 v37, 0xffff0000, v37
	v_pk_add_f32 v[30:31], v[30:31], v[34:35]
	v_pk_add_f32 v[28:29], v[28:29], v[40:41]
	v_pk_add_f32 v[34:35], v[26:27], v[36:37]
	v_pk_add_f32 v[36:37], v[24:25], v[42:43]
	v_cvt_pk_bf16_f32 v24, v28, v29
	v_cvt_pk_bf16_f32 v25, v30, v31
	v_cvt_pk_bf16_f32 v26, v36, v37
	v_cvt_pk_bf16_f32 v27, v34, v35
	global_store_dwordx4 v[38:39], v[24:27], off
	s_nop 1
	v_mul_f32_e32 v24, v29, v29
	v_mul_f32_e32 v25, v31, v31
	v_fmac_f32_e32 v24, v28, v28
	v_fmac_f32_e32 v25, v30, v30
	v_add_f32_e32 v24, v24, v25
	v_mul_f32_e32 v25, v37, v37
	v_fmac_f32_e32 v25, v36, v36
	v_add_f32_e32 v24, v25, v24
	v_mul_f32_e32 v25, v35, v35
	v_fmac_f32_e32 v25, v34, v34
	v_add_f32_e32 v34, v25, v24
	s_waitcnt vmcnt(15)
	v_mov_b32_e32 v24, v228
	v_mov_b32_e32 v25, v229
	v_mov_b32_e32 v26, v230
	v_mov_b32_e32 v27, v231
	v_lshlrev_b32_e32 v28, 16, v24
	v_and_b32_e32 v29, 0xffff0000, v24
	v_lshlrev_b32_e32 v24, 16, v25
	v_and_b32_e32 v25, 0xffff0000, v25
	v_lshlrev_b32_e32 v30, 16, v26
	v_and_b32_e32 v31, 0xffff0000, v26
	v_lshlrev_b32_e32 v26, 16, v27
	v_and_b32_e32 v27, 0xffff0000, v27
	v_pk_add_f32 v[22:23], v[22:23], v[24:25]
	v_pk_add_f32 v[20:21], v[20:21], v[28:29]
	v_pk_add_f32 v[24:25], v[18:19], v[26:27]
	v_pk_add_f32 v[26:27], v[16:17], v[30:31]
	v_cvt_pk_bf16_f32 v16, v20, v21
	v_cvt_pk_bf16_f32 v17, v22, v23
	v_cvt_pk_bf16_f32 v18, v26, v27
	v_cvt_pk_bf16_f32 v19, v24, v25
	global_store_dwordx4 v[38:39], v[16:19], off offset:256
	s_nop 1
	v_mul_f32_e32 v16, v21, v21
	v_mul_f32_e32 v17, v23, v23
	v_fmac_f32_e32 v16, v20, v20
	v_fmac_f32_e32 v17, v22, v22
	v_add_f32_e32 v16, v16, v17
	v_mul_f32_e32 v17, v27, v27
	v_fmac_f32_e32 v17, v26, v26
	v_add_f32_e32 v16, v17, v16
	v_mul_f32_e32 v17, v25, v25
	v_fmac_f32_e32 v17, v24, v24
	v_add_f32_e32 v16, v17, v16
	v_add_f32_e32 v16, v34, v16
	ds_bpermute_b32 v17, v151, v16
	s_waitcnt lgkmcnt(0)
	v_add_f32_e32 v16, v16, v17
	ds_bpermute_b32 v17, v152, v16
	s_and_saveexec_b64 s[8:9], s[44:45]
	s_cbranch_execz .LBB0_858
	v_lshlrev_b64 v[18:19], 6, v[32:33]
	v_lshl_add_u64 v[18:19], s[0:1], 0, v[18:19]
	v_lshl_add_u64 v[18:19], s[30:31], 2, v[18:19]
	s_lshl_b32 s6, s33, 2
	v_lshl_add_u64 v[18:19], v[18:19], 0, s[6:7]
	s_waitcnt lgkmcnt(0)
	v_add_f32_e32 v16, v16, v17
	global_store_dword v[18:19], v16, off
.LBB0_858:
	s_or_b64 exec, exec, s[8:9]
	v_add_u32_e32 v16, 0xb0, v146
	s_waitcnt lgkmcnt(0)
	v_ashrrev_i32_e32 v17, 31, v16
	v_lshlrev_b64 v[18:19], 11, v[16:17]
	v_lshl_add_u64 v[18:19], s[34:35], 0, v[18:19]
	v_lshl_add_u64 v[22:23], v[144:145], 1, v[18:19]
	s_waitcnt vmcnt(15)
	v_mov_b32_e32 v18, v232
	v_mov_b32_e32 v19, v233
	v_mov_b32_e32 v20, v234
	v_mov_b32_e32 v21, v235
	v_lshlrev_b32_e32 v24, 16, v18
	v_and_b32_e32 v25, 0xffff0000, v18
	v_lshlrev_b32_e32 v18, 16, v19
	v_and_b32_e32 v19, 0xffff0000, v19
	v_lshlrev_b32_e32 v26, 16, v20
	v_and_b32_e32 v27, 0xffff0000, v20
	v_lshlrev_b32_e32 v20, 16, v21
	v_and_b32_e32 v21, 0xffff0000, v21
	v_pk_add_f32 v[14:15], v[14:15], v[18:19]
	v_pk_add_f32 v[12:13], v[12:13], v[24:25]
	v_pk_add_f32 v[18:19], v[10:11], v[20:21]
	v_pk_add_f32 v[20:21], v[8:9], v[26:27]
	v_cvt_pk_bf16_f32 v8, v12, v13
	v_cvt_pk_bf16_f32 v9, v14, v15
	v_cvt_pk_bf16_f32 v10, v20, v21
	v_cvt_pk_bf16_f32 v11, v18, v19
	global_store_dwordx4 v[22:23], v[8:11], off
	s_nop 1
	v_mul_f32_e32 v8, v13, v13
	v_mul_f32_e32 v9, v15, v15
	v_fmac_f32_e32 v8, v12, v12
	v_fmac_f32_e32 v9, v14, v14
	v_add_f32_e32 v8, v8, v9
	v_mul_f32_e32 v9, v21, v21
	v_fmac_f32_e32 v9, v20, v20
	v_add_f32_e32 v8, v9, v8
	v_mul_f32_e32 v9, v19, v19
	v_fmac_f32_e32 v9, v18, v18
	v_add_f32_e32 v18, v9, v8
	s_waitcnt vmcnt(15)
	v_mov_b32_e32 v8, v236
	v_mov_b32_e32 v9, v237
	v_mov_b32_e32 v10, v238
	v_mov_b32_e32 v11, v239
	v_lshlrev_b32_e32 v12, 16, v8
	v_and_b32_e32 v13, 0xffff0000, v8
	v_lshlrev_b32_e32 v8, 16, v9
	v_and_b32_e32 v9, 0xffff0000, v9
	v_lshlrev_b32_e32 v14, 16, v10
	v_and_b32_e32 v15, 0xffff0000, v10
	v_lshlrev_b32_e32 v10, 16, v11
	v_and_b32_e32 v11, 0xffff0000, v11
	v_pk_add_f32 v[6:7], v[6:7], v[8:9]
	v_pk_add_f32 v[4:5], v[4:5], v[12:13]
	v_pk_add_f32 v[8:9], v[2:3], v[10:11]
	v_pk_add_f32 v[10:11], v[0:1], v[14:15]
	v_cvt_pk_bf16_f32 v0, v4, v5
	v_cvt_pk_bf16_f32 v1, v6, v7
	v_cvt_pk_bf16_f32 v2, v10, v11
	v_cvt_pk_bf16_f32 v3, v8, v9
	global_store_dwordx4 v[22:23], v[0:3], off offset:256
	s_nop 1
	v_mul_f32_e32 v0, v5, v5
	v_mul_f32_e32 v1, v7, v7
	v_fmac_f32_e32 v0, v4, v4
	v_fmac_f32_e32 v1, v6, v6
	v_add_f32_e32 v0, v0, v1
	v_mul_f32_e32 v1, v11, v11
	v_fmac_f32_e32 v1, v10, v10
	v_add_f32_e32 v0, v1, v0
	v_mul_f32_e32 v1, v9, v9
	v_fmac_f32_e32 v1, v8, v8
	v_add_f32_e32 v0, v1, v0
	v_add_f32_e32 v0, v18, v0
	ds_bpermute_b32 v1, v151, v0
	s_waitcnt lgkmcnt(0)
	v_add_f32_e32 v0, v0, v1
	ds_bpermute_b32 v1, v152, v0
	s_and_saveexec_b64 s[8:9], s[44:45]
	s_cbranch_execz .LBB0_860
	v_lshlrev_b64 v[2:3], 6, v[16:17]
	v_lshl_add_u64 v[2:3], s[0:1], 0, v[2:3]
	v_lshl_add_u64 v[2:3], s[30:31], 2, v[2:3]
	s_lshl_b32 s6, s33, 2
	v_lshl_add_u64 v[2:3], v[2:3], 0, s[6:7]
	s_waitcnt lgkmcnt(0)
	v_add_f32_e32 v0, v0, v1
	global_store_dword v[2:3], v0, off

.LBB0_1229:
	v_lshl_add_u32 v146, s26, 8, v148
	v_lshl_add_u32 v144, s6, 8, v150
	v_ashrrev_i32_e32 v147, 31, v146
	v_ashrrev_i32_e32 v145, 31, v144
	v_lshlrev_b64 v[154:155], 10, v[146:147]
	v_lshl_add_u64 v[154:155], v[154:155], 0, v[144:145]
	v_lshlrev_b64 v[158:159], 1, v[154:155]
	global_load_dwordx4 v[166:169], v158, s[34:35]
	s_nop 0
	global_load_dwordx4 v[170:173], v158, s[34:35] offset:256
	v_add_u32_e32 v178, 0x8000, v158
	global_load_dwordx4 v[174:177], v178, s[34:35]
	s_nop 0
	global_load_dwordx4 v[178:181], v178, s[34:35] offset:256
	v_add_u32_e32 v186, 0x10000, v158
	global_load_dwordx4 v[182:185], v186, s[34:35]
	s_nop 0
	global_load_dwordx4 v[186:189], v186, s[34:35] offset:256
	v_add_u32_e32 v200, 0x18000, v158
	global_load_dwordx4 v[190:193], v200, s[34:35]
	s_nop 0
	global_load_dwordx4 v[200:203], v200, s[34:35] offset:256
	v_add_u32_e32 v208, 0x40000, v158
	global_load_dwordx4 v[204:207], v208, s[34:35]
	s_nop 0
	global_load_dwordx4 v[208:211], v208, s[34:35] offset:256
	v_add_u32_e32 v216, 0x48000, v158
	global_load_dwordx4 v[212:215], v216, s[34:35]
	s_nop 0
	global_load_dwordx4 v[216:219], v216, s[34:35] offset:256
	v_add_u32_e32 v224, 0x50000, v158
	global_load_dwordx4 v[220:223], v224, s[34:35]
	s_nop 0
	global_load_dwordx4 v[224:227], v224, s[34:35] offset:256
	v_add_u32_e32 v232, 0x58000, v158
	global_load_dwordx4 v[228:231], v232, s[34:35]
	s_nop 0
	global_load_dwordx4 v[232:235], v232, s[34:35] offset:256
	v_lshl_add_u64 v[160:161], s[34:35], 0, v[158:159]
	v_lshl_add_u64 v[158:159], s[96:97], 0, v[158:159]
	s_lshl_b32 s26, s6, 2
	s_ashr_i32 s27, s26, 31
	s_waitcnt vmcnt(15)
	v_mov_b32_e32 v154, v166
	v_mov_b32_e32 v155, v167
	v_mov_b32_e32 v156, v168
	v_mov_b32_e32 v157, v169
	v_lshlrev_b32_e32 v162, 16, v154
	v_and_b32_e32 v163, 0xffff0000, v154
	v_lshlrev_b32_e32 v154, 16, v155
	v_and_b32_e32 v155, 0xffff0000, v155
	v_lshlrev_b32_e32 v164, 16, v156
	v_and_b32_e32 v165, 0xffff0000, v156
	v_lshlrev_b32_e32 v156, 16, v157
	v_and_b32_e32 v157, 0xffff0000, v157
	v_pk_add_f32 v[126:127], v[126:127], v[154:155]
	v_pk_add_f32 v[124:125], v[124:125], v[162:163]
	v_pk_add_f32 v[154:155], v[122:123], v[156:157]
	v_pk_add_f32 v[156:157], v[120:121], v[164:165]
	v_cvt_pk_bf16_f32 v120, v124, v125
	v_cvt_pk_bf16_f32 v121, v126, v127
	v_cvt_pk_bf16_f32 v122, v156, v157
	v_cvt_pk_bf16_f32 v123, v154, v155
	global_store_dwordx4 v[158:159], v[120:123], off
	s_nop 1
	v_mul_f32_e32 v120, v125, v125
	v_mul_f32_e32 v121, v127, v127
	v_fmac_f32_e32 v120, v124, v124
	v_fmac_f32_e32 v121, v126, v126
	v_add_f32_e32 v120, v120, v121
	v_mul_f32_e32 v121, v157, v157
	v_fmac_f32_e32 v121, v156, v156
	v_add_f32_e32 v120, v121, v120
	v_mul_f32_e32 v121, v155, v155
	v_fmac_f32_e32 v121, v154, v154
	v_add_f32_e32 v154, v121, v120
	s_waitcnt vmcnt(15)
	v_mov_b32_e32 v120, v170
	v_mov_b32_e32 v121, v171
	v_mov_b32_e32 v122, v172
	v_mov_b32_e32 v123, v173
	v_lshlrev_b32_e32 v124, 16, v120
	v_and_b32_e32 v125, 0xffff0000, v120
	v_lshlrev_b32_e32 v120, 16, v121
	v_and_b32_e32 v121, 0xffff0000, v121
	v_lshlrev_b32_e32 v126, 16, v122
	v_and_b32_e32 v127, 0xffff0000, v122
	v_lshlrev_b32_e32 v122, 16, v123
	v_and_b32_e32 v123, 0xffff0000, v123
	v_pk_add_f32 v[118:119], v[118:119], v[120:121]
	v_pk_add_f32 v[116:117], v[116:117], v[124:125]
	v_pk_add_f32 v[120:121], v[114:115], v[122:123]
	v_pk_add_f32 v[122:123], v[112:113], v[126:127]
	v_cvt_pk_bf16_f32 v112, v116, v117
	v_cvt_pk_bf16_f32 v113, v118, v119
	v_cvt_pk_bf16_f32 v114, v122, v123
	v_cvt_pk_bf16_f32 v115, v120, v121
	global_store_dwordx4 v[158:159], v[112:115], off offset:256
	s_nop 1
	v_mul_f32_e32 v112, v117, v117
	v_mul_f32_e32 v113, v119, v119
	v_fmac_f32_e32 v112, v116, v116
	v_fmac_f32_e32 v113, v118, v118
	v_add_f32_e32 v112, v112, v113
	v_mul_f32_e32 v113, v123, v123
	v_fmac_f32_e32 v113, v122, v122
	v_add_f32_e32 v112, v113, v112
	v_mul_f32_e32 v113, v121, v121
	v_fmac_f32_e32 v113, v120, v120
	v_add_f32_e32 v112, v113, v112
	v_add_f32_e32 v112, v154, v112
	ds_bpermute_b32 v113, v198, v112
	s_waitcnt lgkmcnt(0)
	v_add_f32_e32 v112, v112, v113
	ds_bpermute_b32 v113, v199, v112
	s_and_saveexec_b64 s[8:9], s[44:45]
	s_cbranch_execz .LBB0_1231
	v_lshlrev_b64 v[114:115], 6, v[146:147]
	v_lshl_add_u64 v[114:115], s[0:1], 0, v[114:115]
	v_lshl_add_u64 v[114:115], s[26:27], 2, v[114:115]
	s_lshl_b32 s6, s37, 2
	v_lshl_add_u64 v[114:115], v[114:115], 0, s[6:7]
	s_waitcnt lgkmcnt(0)
	v_add_f32_e32 v112, v112, v113
	global_store_dword v[114:115], v112, off
.LBB0_1231:
	s_or_b64 exec, exec, s[8:9]
	v_or_b32_e32 v112, 16, v146
	s_waitcnt lgkmcnt(0)
	v_ashrrev_i32_e32 v113, 31, v112
	v_lshlrev_b64 v[114:115], 10, v[112:113]
	v_lshl_add_u64 v[114:115], v[114:115], 0, v[144:145]
	v_lshlrev_b64 v[118:119], 1, v[114:115]
	v_lshl_add_u64 v[120:121], s[34:35], 0, v[118:119]
	v_lshl_add_u64 v[118:119], s[96:97], 0, v[118:119]
	s_waitcnt vmcnt(15)
	v_mov_b32_e32 v114, v174
	v_mov_b32_e32 v115, v175
	v_mov_b32_e32 v116, v176
	v_mov_b32_e32 v117, v177
	v_lshlrev_b32_e32 v122, 16, v114
	v_and_b32_e32 v123, 0xffff0000, v114
	v_lshlrev_b32_e32 v114, 16, v115
	v_and_b32_e32 v115, 0xffff0000, v115
	v_lshlrev_b32_e32 v124, 16, v116
	v_and_b32_e32 v125, 0xffff0000, v116
	v_lshlrev_b32_e32 v116, 16, v117
	v_and_b32_e32 v117, 0xffff0000, v117
	v_pk_add_f32 v[110:111], v[110:111], v[114:115]
	v_pk_add_f32 v[108:109], v[108:109], v[122:123]
	v_pk_add_f32 v[114:115], v[106:107], v[116:117]
	v_pk_add_f32 v[116:117], v[104:105], v[124:125]
	v_cvt_pk_bf16_f32 v104, v108, v109
	v_cvt_pk_bf16_f32 v105, v110, v111
	v_cvt_pk_bf16_f32 v106, v116, v117
	v_cvt_pk_bf16_f32 v107, v114, v115
	global_store_dwordx4 v[118:119], v[104:107], off
	s_nop 1
	v_mul_f32_e32 v104, v109, v109
	v_mul_f32_e32 v105, v111, v111
	v_fmac_f32_e32 v104, v108, v108
	v_fmac_f32_e32 v105, v110, v110
	v_add_f32_e32 v104, v104, v105
	v_mul_f32_e32 v105, v117, v117
	v_fmac_f32_e32 v105, v116, v116
	v_add_f32_e32 v104, v105, v104
	v_mul_f32_e32 v105, v115, v115
	v_fmac_f32_e32 v105, v114, v114
	v_add_f32_e32 v114, v105, v104
	s_waitcnt vmcnt(15)
	v_mov_b32_e32 v104, v178
	v_mov_b32_e32 v105, v179
	v_mov_b32_e32 v106, v180
	v_mov_b32_e32 v107, v181
	v_lshlrev_b32_e32 v108, 16, v104
	v_and_b32_e32 v109, 0xffff0000, v104
	v_lshlrev_b32_e32 v104, 16, v105
	v_and_b32_e32 v105, 0xffff0000, v105
	v_lshlrev_b32_e32 v110, 16, v106
	v_and_b32_e32 v111, 0xffff0000, v106
	v_lshlrev_b32_e32 v106, 16, v107
	v_and_b32_e32 v107, 0xffff0000, v107
	v_pk_add_f32 v[102:103], v[102:103], v[104:105]
	v_pk_add_f32 v[100:101], v[100:101], v[108:109]
	v_pk_add_f32 v[104:105], v[98:99], v[106:107]
	v_pk_add_f32 v[106:107], v[96:97], v[110:111]
	v_cvt_pk_bf16_f32 v96, v100, v101
	v_cvt_pk_bf16_f32 v97, v102, v103
	v_cvt_pk_bf16_f32 v98, v106, v107
	v_cvt_pk_bf16_f32 v99, v104, v105
	global_store_dwordx4 v[118:119], v[96:99], off offset:256
	s_nop 1
	v_mul_f32_e32 v96, v101, v101
	v_mul_f32_e32 v97, v103, v103
	v_fmac_f32_e32 v96, v100, v100
	v_fmac_f32_e32 v97, v102, v102
	v_add_f32_e32 v96, v96, v97
	v_mul_f32_e32 v97, v107, v107
	v_fmac_f32_e32 v97, v106, v106
	v_add_f32_e32 v96, v97, v96
	v_mul_f32_e32 v97, v105, v105
	v_fmac_f32_e32 v97, v104, v104
	v_add_f32_e32 v96, v97, v96
	v_add_f32_e32 v96, v114, v96
	ds_bpermute_b32 v97, v198, v96
	s_waitcnt lgkmcnt(0)
	v_add_f32_e32 v96, v96, v97
	ds_bpermute_b32 v97, v199, v96
	s_and_saveexec_b64 s[8:9], s[44:45]
	s_cbranch_execz .LBB0_1233
	v_lshlrev_b64 v[98:99], 6, v[112:113]
	v_lshl_add_u64 v[98:99], s[0:1], 0, v[98:99]
	v_lshl_add_u64 v[98:99], s[26:27], 2, v[98:99]
	s_lshl_b32 s6, s37, 2
	v_lshl_add_u64 v[98:99], v[98:99], 0, s[6:7]
	s_waitcnt lgkmcnt(0)
	v_add_f32_e32 v96, v96, v97
	global_store_dword v[98:99], v96, off
.LBB0_1233:
	s_or_b64 exec, exec, s[8:9]
	v_or_b32_e32 v96, 32, v146
	s_waitcnt lgkmcnt(0)
	v_ashrrev_i32_e32 v97, 31, v96
	v_lshlrev_b64 v[98:99], 10, v[96:97]
	v_lshl_add_u64 v[98:99], v[98:99], 0, v[144:145]
	v_lshlrev_b64 v[102:103], 1, v[98:99]
	v_lshl_add_u64 v[104:105], s[34:35], 0, v[102:103]
	v_lshl_add_u64 v[102:103], s[96:97], 0, v[102:103]
	s_waitcnt vmcnt(15)
	v_mov_b32_e32 v98, v182
	v_mov_b32_e32 v99, v183
	v_mov_b32_e32 v100, v184
	v_mov_b32_e32 v101, v185
	v_lshlrev_b32_e32 v106, 16, v98
	v_and_b32_e32 v107, 0xffff0000, v98
	v_lshlrev_b32_e32 v98, 16, v99
	v_and_b32_e32 v99, 0xffff0000, v99
	v_lshlrev_b32_e32 v108, 16, v100
	v_and_b32_e32 v109, 0xffff0000, v100
	v_lshlrev_b32_e32 v100, 16, v101
	v_and_b32_e32 v101, 0xffff0000, v101
	v_pk_add_f32 v[94:95], v[94:95], v[98:99]
	v_pk_add_f32 v[92:93], v[92:93], v[106:107]
	v_pk_add_f32 v[98:99], v[90:91], v[100:101]
	v_pk_add_f32 v[100:101], v[88:89], v[108:109]
	v_cvt_pk_bf16_f32 v88, v92, v93
	v_cvt_pk_bf16_f32 v89, v94, v95
	v_cvt_pk_bf16_f32 v90, v100, v101
	v_cvt_pk_bf16_f32 v91, v98, v99
	global_store_dwordx4 v[102:103], v[88:91], off
	s_nop 1
	v_mul_f32_e32 v88, v93, v93
	v_mul_f32_e32 v89, v95, v95
	v_fmac_f32_e32 v88, v92, v92
	v_fmac_f32_e32 v89, v94, v94
	v_add_f32_e32 v88, v88, v89
	v_mul_f32_e32 v89, v101, v101
	v_fmac_f32_e32 v89, v100, v100
	v_add_f32_e32 v88, v89, v88
	v_mul_f32_e32 v89, v99, v99
	v_fmac_f32_e32 v89, v98, v98
	v_add_f32_e32 v98, v89, v88
	s_waitcnt vmcnt(15)
	v_mov_b32_e32 v88, v186
	v_mov_b32_e32 v89, v187
	v_mov_b32_e32 v90, v188
	v_mov_b32_e32 v91, v189
	v_lshlrev_b32_e32 v92, 16, v88
	v_and_b32_e32 v93, 0xffff0000, v88
	v_lshlrev_b32_e32 v88, 16, v89
	v_and_b32_e32 v89, 0xffff0000, v89
	v_lshlrev_b32_e32 v94, 16, v90
	v_and_b32_e32 v95, 0xffff0000, v90
	v_lshlrev_b32_e32 v90, 16, v91
	v_and_b32_e32 v91, 0xffff0000, v91
	v_pk_add_f32 v[86:87], v[86:87], v[88:89]
	v_pk_add_f32 v[84:85], v[84:85], v[92:93]
	v_pk_add_f32 v[88:89], v[82:83], v[90:91]
	v_pk_add_f32 v[90:91], v[80:81], v[94:95]
	v_cvt_pk_bf16_f32 v80, v84, v85
	v_cvt_pk_bf16_f32 v81, v86, v87
	v_cvt_pk_bf16_f32 v82, v90, v91
	v_cvt_pk_bf16_f32 v83, v88, v89
	global_store_dwordx4 v[102:103], v[80:83], off offset:256
	s_nop 1
	v_mul_f32_e32 v80, v85, v85
	v_mul_f32_e32 v81, v87, v87
	v_fmac_f32_e32 v80, v84, v84
	v_fmac_f32_e32 v81, v86, v86
	v_add_f32_e32 v80, v80, v81
	v_mul_f32_e32 v81, v91, v91
	v_fmac_f32_e32 v81, v90, v90
	v_add_f32_e32 v80, v81, v80
	v_mul_f32_e32 v81, v89, v89
	v_fmac_f32_e32 v81, v88, v88
	v_add_f32_e32 v80, v81, v80
	v_add_f32_e32 v80, v98, v80
	ds_bpermute_b32 v81, v198, v80
	s_waitcnt lgkmcnt(0)
	v_add_f32_e32 v80, v80, v81
	ds_bpermute_b32 v81, v199, v80
	s_and_saveexec_b64 s[8:9], s[44:45]
	s_cbranch_execz .LBB0_1235
	v_lshlrev_b64 v[82:83], 6, v[96:97]
	v_lshl_add_u64 v[82:83], s[0:1], 0, v[82:83]
	v_lshl_add_u64 v[82:83], s[26:27], 2, v[82:83]
	s_lshl_b32 s6, s37, 2
	v_lshl_add_u64 v[82:83], v[82:83], 0, s[6:7]
	s_waitcnt lgkmcnt(0)
	v_add_f32_e32 v80, v80, v81
	global_store_dword v[82:83], v80, off
.LBB0_1235:
	s_or_b64 exec, exec, s[8:9]
	v_or_b32_e32 v80, 48, v146
	s_waitcnt lgkmcnt(0)
	v_ashrrev_i32_e32 v81, 31, v80
	v_lshlrev_b64 v[82:83], 10, v[80:81]
	v_lshl_add_u64 v[82:83], v[82:83], 0, v[144:145]
	v_lshlrev_b64 v[86:87], 1, v[82:83]
	v_lshl_add_u64 v[88:89], s[34:35], 0, v[86:87]
	v_lshl_add_u64 v[86:87], s[96:97], 0, v[86:87]
	s_waitcnt vmcnt(15)
	v_mov_b32_e32 v82, v190
	v_mov_b32_e32 v83, v191
	v_mov_b32_e32 v84, v192
	v_mov_b32_e32 v85, v193
	v_lshlrev_b32_e32 v90, 16, v82
	v_and_b32_e32 v91, 0xffff0000, v82
	v_lshlrev_b32_e32 v82, 16, v83
	v_and_b32_e32 v83, 0xffff0000, v83
	v_lshlrev_b32_e32 v92, 16, v84
	v_and_b32_e32 v93, 0xffff0000, v84
	v_lshlrev_b32_e32 v84, 16, v85
	v_and_b32_e32 v85, 0xffff0000, v85
	v_pk_add_f32 v[78:79], v[78:79], v[82:83]
	v_pk_add_f32 v[76:77], v[76:77], v[90:91]
	v_pk_add_f32 v[82:83], v[74:75], v[84:85]
	v_pk_add_f32 v[84:85], v[72:73], v[92:93]
	v_cvt_pk_bf16_f32 v72, v76, v77
	v_cvt_pk_bf16_f32 v73, v78, v79
	v_cvt_pk_bf16_f32 v74, v84, v85
	v_cvt_pk_bf16_f32 v75, v82, v83
	global_store_dwordx4 v[86:87], v[72:75], off
	s_nop 1
	v_mul_f32_e32 v72, v77, v77
	v_mul_f32_e32 v73, v79, v79
	v_fmac_f32_e32 v72, v76, v76
	v_fmac_f32_e32 v73, v78, v78
	v_add_f32_e32 v72, v72, v73
	v_mul_f32_e32 v73, v85, v85
	v_fmac_f32_e32 v73, v84, v84
	v_add_f32_e32 v72, v73, v72
	v_mul_f32_e32 v73, v83, v83
	v_fmac_f32_e32 v73, v82, v82
	v_add_f32_e32 v82, v73, v72
	s_waitcnt vmcnt(15)
	v_mov_b32_e32 v72, v200
	v_mov_b32_e32 v73, v201
	v_mov_b32_e32 v74, v202
	v_mov_b32_e32 v75, v203
	v_lshlrev_b32_e32 v76, 16, v72
	v_and_b32_e32 v77, 0xffff0000, v72
	v_lshlrev_b32_e32 v72, 16, v73
	v_and_b32_e32 v73, 0xffff0000, v73
	v_lshlrev_b32_e32 v78, 16, v74
	v_and_b32_e32 v79, 0xffff0000, v74
	v_lshlrev_b32_e32 v74, 16, v75
	v_and_b32_e32 v75, 0xffff0000, v75
	v_pk_add_f32 v[70:71], v[70:71], v[72:73]
	v_pk_add_f32 v[68:69], v[68:69], v[76:77]
	v_pk_add_f32 v[72:73], v[66:67], v[74:75]
	v_pk_add_f32 v[74:75], v[64:65], v[78:79]
	v_cvt_pk_bf16_f32 v64, v68, v69
	v_cvt_pk_bf16_f32 v65, v70, v71
	v_cvt_pk_bf16_f32 v66, v74, v75
	v_cvt_pk_bf16_f32 v67, v72, v73
	global_store_dwordx4 v[86:87], v[64:67], off offset:256
	s_nop 1
	v_mul_f32_e32 v64, v69, v69
	v_mul_f32_e32 v65, v71, v71
	v_fmac_f32_e32 v64, v68, v68
	v_fmac_f32_e32 v65, v70, v70
	v_add_f32_e32 v64, v64, v65
	v_mul_f32_e32 v65, v75, v75
	v_fmac_f32_e32 v65, v74, v74
	v_add_f32_e32 v64, v65, v64
	v_mul_f32_e32 v65, v73, v73
	v_fmac_f32_e32 v65, v72, v72
	v_add_f32_e32 v64, v65, v64
	v_add_f32_e32 v64, v82, v64
	ds_bpermute_b32 v65, v198, v64
	s_waitcnt lgkmcnt(0)
	v_add_f32_e32 v64, v64, v65
	ds_bpermute_b32 v65, v199, v64
	s_and_saveexec_b64 s[8:9], s[44:45]
	s_cbranch_execz .LBB0_1237
	v_lshlrev_b64 v[66:67], 6, v[80:81]
	v_lshl_add_u64 v[66:67], s[0:1], 0, v[66:67]
	v_lshl_add_u64 v[66:67], s[26:27], 2, v[66:67]
	s_lshl_b32 s6, s37, 2
	v_lshl_add_u64 v[66:67], v[66:67], 0, s[6:7]
	s_waitcnt lgkmcnt(0)
	v_add_f32_e32 v64, v64, v65
	global_store_dword v[66:67], v64, off
.LBB0_1237:
	s_or_b64 exec, exec, s[8:9]
	v_add_u32_e32 v64, 0x80, v146
	s_waitcnt lgkmcnt(0)
	v_ashrrev_i32_e32 v65, 31, v64
	v_lshlrev_b64 v[66:67], 10, v[64:65]
	v_lshl_add_u64 v[66:67], v[66:67], 0, v[144:145]
	v_lshlrev_b64 v[70:71], 1, v[66:67]
	v_lshl_add_u64 v[72:73], s[34:35], 0, v[70:71]
	v_lshl_add_u64 v[70:71], s[96:97], 0, v[70:71]
	s_waitcnt vmcnt(15)
	v_mov_b32_e32 v66, v204
	v_mov_b32_e32 v67, v205
	v_mov_b32_e32 v68, v206
	v_mov_b32_e32 v69, v207
	v_lshlrev_b32_e32 v74, 16, v66
	v_and_b32_e32 v75, 0xffff0000, v66
	v_lshlrev_b32_e32 v66, 16, v67
	v_and_b32_e32 v67, 0xffff0000, v67
	v_lshlrev_b32_e32 v76, 16, v68
	v_and_b32_e32 v77, 0xffff0000, v68
	v_lshlrev_b32_e32 v68, 16, v69
	v_and_b32_e32 v69, 0xffff0000, v69
	v_pk_add_f32 v[62:63], v[62:63], v[66:67]
	v_pk_add_f32 v[60:61], v[60:61], v[74:75]
	v_pk_add_f32 v[66:67], v[58:59], v[68:69]
	v_pk_add_f32 v[68:69], v[56:57], v[76:77]
	v_cvt_pk_bf16_f32 v56, v60, v61
	v_cvt_pk_bf16_f32 v57, v62, v63
	v_cvt_pk_bf16_f32 v58, v68, v69
	v_cvt_pk_bf16_f32 v59, v66, v67
	global_store_dwordx4 v[70:71], v[56:59], off
	s_nop 1
	v_mul_f32_e32 v56, v61, v61
	v_mul_f32_e32 v57, v63, v63
	v_fmac_f32_e32 v56, v60, v60
	v_fmac_f32_e32 v57, v62, v62
	v_add_f32_e32 v56, v56, v57
	v_mul_f32_e32 v57, v69, v69
	v_fmac_f32_e32 v57, v68, v68
	v_add_f32_e32 v56, v57, v56
	v_mul_f32_e32 v57, v67, v67
	v_fmac_f32_e32 v57, v66, v66
	v_add_f32_e32 v66, v57, v56
	s_waitcnt vmcnt(15)
	v_mov_b32_e32 v56, v208
	v_mov_b32_e32 v57, v209
	v_mov_b32_e32 v58, v210
	v_mov_b32_e32 v59, v211
	v_lshlrev_b32_e32 v60, 16, v56
	v_and_b32_e32 v61, 0xffff0000, v56
	v_lshlrev_b32_e32 v56, 16, v57
	v_and_b32_e32 v57, 0xffff0000, v57
	v_lshlrev_b32_e32 v62, 16, v58
	v_and_b32_e32 v63, 0xffff0000, v58
	v_lshlrev_b32_e32 v58, 16, v59
	v_and_b32_e32 v59, 0xffff0000, v59
	v_pk_add_f32 v[54:55], v[54:55], v[56:57]
	v_pk_add_f32 v[52:53], v[52:53], v[60:61]
	v_pk_add_f32 v[56:57], v[50:51], v[58:59]
	v_pk_add_f32 v[58:59], v[48:49], v[62:63]
	v_cvt_pk_bf16_f32 v48, v52, v53
	v_cvt_pk_bf16_f32 v49, v54, v55
	v_cvt_pk_bf16_f32 v50, v58, v59
	v_cvt_pk_bf16_f32 v51, v56, v57
	global_store_dwordx4 v[70:71], v[48:51], off offset:256
	s_nop 1
	v_mul_f32_e32 v48, v53, v53
	v_mul_f32_e32 v49, v55, v55
	v_fmac_f32_e32 v48, v52, v52
	v_fmac_f32_e32 v49, v54, v54
	v_add_f32_e32 v48, v48, v49
	v_mul_f32_e32 v49, v59, v59
	v_fmac_f32_e32 v49, v58, v58
	v_add_f32_e32 v48, v49, v48
	v_mul_f32_e32 v49, v57, v57
	v_fmac_f32_e32 v49, v56, v56
	v_add_f32_e32 v48, v49, v48
	v_add_f32_e32 v48, v66, v48
	ds_bpermute_b32 v49, v198, v48
	s_waitcnt lgkmcnt(0)
	v_add_f32_e32 v48, v48, v49
	ds_bpermute_b32 v49, v199, v48
	s_and_saveexec_b64 s[8:9], s[44:45]
	s_cbranch_execz .LBB0_1239
	v_lshlrev_b64 v[50:51], 6, v[64:65]
	v_lshl_add_u64 v[50:51], s[0:1], 0, v[50:51]
	v_lshl_add_u64 v[50:51], s[26:27], 2, v[50:51]
	s_lshl_b32 s6, s37, 2
	v_lshl_add_u64 v[50:51], v[50:51], 0, s[6:7]
	s_waitcnt lgkmcnt(0)
	v_add_f32_e32 v48, v48, v49
	global_store_dword v[50:51], v48, off
.LBB0_1239:
	s_or_b64 exec, exec, s[8:9]
	v_add_u32_e32 v48, 0x90, v146
	s_waitcnt lgkmcnt(0)
	v_ashrrev_i32_e32 v49, 31, v48
	v_lshlrev_b64 v[50:51], 10, v[48:49]
	v_lshl_add_u64 v[50:51], v[50:51], 0, v[144:145]
	v_lshlrev_b64 v[54:55], 1, v[50:51]
	v_lshl_add_u64 v[56:57], s[34:35], 0, v[54:55]
	v_lshl_add_u64 v[54:55], s[96:97], 0, v[54:55]
	s_waitcnt vmcnt(15)
	v_mov_b32_e32 v50, v212
	v_mov_b32_e32 v51, v213
	v_mov_b32_e32 v52, v214
	v_mov_b32_e32 v53, v215
	v_lshlrev_b32_e32 v58, 16, v50
	v_and_b32_e32 v59, 0xffff0000, v50
	v_lshlrev_b32_e32 v50, 16, v51
	v_and_b32_e32 v51, 0xffff0000, v51
	v_lshlrev_b32_e32 v60, 16, v52
	v_and_b32_e32 v61, 0xffff0000, v52
	v_lshlrev_b32_e32 v52, 16, v53
	v_and_b32_e32 v53, 0xffff0000, v53
	v_pk_add_f32 v[46:47], v[46:47], v[50:51]
	v_pk_add_f32 v[44:45], v[44:45], v[58:59]
	v_pk_add_f32 v[50:51], v[42:43], v[52:53]
	v_pk_add_f32 v[52:53], v[40:41], v[60:61]
	v_cvt_pk_bf16_f32 v40, v44, v45
	v_cvt_pk_bf16_f32 v41, v46, v47
	v_cvt_pk_bf16_f32 v42, v52, v53
	v_cvt_pk_bf16_f32 v43, v50, v51
	global_store_dwordx4 v[54:55], v[40:43], off
	s_nop 1
	v_mul_f32_e32 v40, v45, v45
	v_mul_f32_e32 v41, v47, v47
	v_fmac_f32_e32 v40, v44, v44
	v_fmac_f32_e32 v41, v46, v46
	v_add_f32_e32 v40, v40, v41
	v_mul_f32_e32 v41, v53, v53
	v_fmac_f32_e32 v41, v52, v52
	v_add_f32_e32 v40, v41, v40
	v_mul_f32_e32 v41, v51, v51
	v_fmac_f32_e32 v41, v50, v50
	v_add_f32_e32 v50, v41, v40
	s_waitcnt vmcnt(15)
	v_mov_b32_e32 v40, v216
	v_mov_b32_e32 v41, v217
	v_mov_b32_e32 v42, v218
	v_mov_b32_e32 v43, v219
	v_lshlrev_b32_e32 v44, 16, v40
	v_and_b32_e32 v45, 0xffff0000, v40
	v_lshlrev_b32_e32 v40, 16, v41
	v_and_b32_e32 v41, 0xffff0000, v41
	v_lshlrev_b32_e32 v46, 16, v42
	v_and_b32_e32 v47, 0xffff0000, v42
	v_lshlrev_b32_e32 v42, 16, v43
	v_and_b32_e32 v43, 0xffff0000, v43
	v_pk_add_f32 v[38:39], v[38:39], v[40:41]
	v_pk_add_f32 v[36:37], v[36:37], v[44:45]
	v_pk_add_f32 v[40:41], v[34:35], v[42:43]
	v_pk_add_f32 v[42:43], v[32:33], v[46:47]
	v_cvt_pk_bf16_f32 v32, v36, v37
	v_cvt_pk_bf16_f32 v33, v38, v39
	v_cvt_pk_bf16_f32 v34, v42, v43
	v_cvt_pk_bf16_f32 v35, v40, v41
	global_store_dwordx4 v[54:55], v[32:35], off offset:256
	s_nop 1
	v_mul_f32_e32 v32, v37, v37
	v_mul_f32_e32 v33, v39, v39
	v_fmac_f32_e32 v32, v36, v36
	v_fmac_f32_e32 v33, v38, v38
	v_add_f32_e32 v32, v32, v33
	v_mul_f32_e32 v33, v43, v43
	v_fmac_f32_e32 v33, v42, v42
	v_add_f32_e32 v32, v33, v32
	v_mul_f32_e32 v33, v41, v41
	v_fmac_f32_e32 v33, v40, v40
	v_add_f32_e32 v32, v33, v32
	v_add_f32_e32 v32, v50, v32
	ds_bpermute_b32 v33, v198, v32
	s_waitcnt lgkmcnt(0)
	v_add_f32_e32 v32, v32, v33
	ds_bpermute_b32 v33, v199, v32
	s_and_saveexec_b64 s[8:9], s[44:45]
	s_cbranch_execz .LBB0_1241
	v_lshlrev_b64 v[34:35], 6, v[48:49]
	v_lshl_add_u64 v[34:35], s[0:1], 0, v[34:35]
	v_lshl_add_u64 v[34:35], s[26:27], 2, v[34:35]
	s_lshl_b32 s6, s37, 2
	v_lshl_add_u64 v[34:35], v[34:35], 0, s[6:7]
	s_waitcnt lgkmcnt(0)
	v_add_f32_e32 v32, v32, v33
	global_store_dword v[34:35], v32, off
.LBB0_1241:
	s_or_b64 exec, exec, s[8:9]
	v_add_u32_e32 v32, 0xa0, v146
	s_waitcnt lgkmcnt(0)
	v_ashrrev_i32_e32 v33, 31, v32
	v_lshlrev_b64 v[34:35], 10, v[32:33]
	v_lshl_add_u64 v[34:35], v[34:35], 0, v[144:145]
	v_lshlrev_b64 v[38:39], 1, v[34:35]
	v_lshl_add_u64 v[40:41], s[34:35], 0, v[38:39]
	v_lshl_add_u64 v[38:39], s[96:97], 0, v[38:39]
	s_waitcnt vmcnt(15)
	v_mov_b32_e32 v34, v220
	v_mov_b32_e32 v35, v221
	v_mov_b32_e32 v36, v222
	v_mov_b32_e32 v37, v223
	v_lshlrev_b32_e32 v42, 16, v34
	v_and_b32_e32 v43, 0xffff0000, v34
	v_lshlrev_b32_e32 v34, 16, v35
	v_and_b32_e32 v35, 0xffff0000, v35
	v_lshlrev_b32_e32 v44, 16, v36
	v_and_b32_e32 v45, 0xffff0000, v36
	v_lshlrev_b32_e32 v36, 16, v37
	v_and_b32_e32 v37, 0xffff0000, v37
	v_pk_add_f32 v[30:31], v[30:31], v[34:35]
	v_pk_add_f32 v[28:29], v[28:29], v[42:43]
	v_pk_add_f32 v[34:35], v[26:27], v[36:37]
	v_pk_add_f32 v[36:37], v[24:25], v[44:45]
	v_cvt_pk_bf16_f32 v24, v28, v29
	v_cvt_pk_bf16_f32 v25, v30, v31
	v_cvt_pk_bf16_f32 v26, v36, v37
	v_cvt_pk_bf16_f32 v27, v34, v35
	global_store_dwordx4 v[38:39], v[24:27], off
	s_nop 1
	v_mul_f32_e32 v24, v29, v29
	v_mul_f32_e32 v25, v31, v31
	v_fmac_f32_e32 v24, v28, v28
	v_fmac_f32_e32 v25, v30, v30
	v_add_f32_e32 v24, v24, v25
	v_mul_f32_e32 v25, v37, v37
	v_fmac_f32_e32 v25, v36, v36
	v_add_f32_e32 v24, v25, v24
	v_mul_f32_e32 v25, v35, v35
	v_fmac_f32_e32 v25, v34, v34
	v_add_f32_e32 v34, v25, v24
	s_waitcnt vmcnt(15)
	v_mov_b32_e32 v24, v224
	v_mov_b32_e32 v25, v225
	v_mov_b32_e32 v26, v226
	v_mov_b32_e32 v27, v227
	v_lshlrev_b32_e32 v28, 16, v24
	v_and_b32_e32 v29, 0xffff0000, v24
	v_lshlrev_b32_e32 v24, 16, v25
	v_and_b32_e32 v25, 0xffff0000, v25
	v_lshlrev_b32_e32 v30, 16, v26
	v_and_b32_e32 v31, 0xffff0000, v26
	v_lshlrev_b32_e32 v26, 16, v27
	v_and_b32_e32 v27, 0xffff0000, v27
	v_pk_add_f32 v[22:23], v[22:23], v[24:25]
	v_pk_add_f32 v[20:21], v[20:21], v[28:29]
	v_pk_add_f32 v[24:25], v[18:19], v[26:27]
	v_pk_add_f32 v[26:27], v[16:17], v[30:31]
	v_cvt_pk_bf16_f32 v16, v20, v21
	v_cvt_pk_bf16_f32 v17, v22, v23
	v_cvt_pk_bf16_f32 v18, v26, v27
	v_cvt_pk_bf16_f32 v19, v24, v25
	global_store_dwordx4 v[38:39], v[16:19], off offset:256
	s_nop 1
	v_mul_f32_e32 v16, v21, v21
	v_mul_f32_e32 v17, v23, v23
	v_fmac_f32_e32 v16, v20, v20
	v_fmac_f32_e32 v17, v22, v22
	v_add_f32_e32 v16, v16, v17
	v_mul_f32_e32 v17, v27, v27
	v_fmac_f32_e32 v17, v26, v26
	v_add_f32_e32 v16, v17, v16
	v_mul_f32_e32 v17, v25, v25
	v_fmac_f32_e32 v17, v24, v24
	v_add_f32_e32 v16, v17, v16
	v_add_f32_e32 v16, v34, v16
	ds_bpermute_b32 v17, v198, v16
	s_waitcnt lgkmcnt(0)
	v_add_f32_e32 v16, v16, v17
	ds_bpermute_b32 v17, v199, v16
	s_and_saveexec_b64 s[8:9], s[44:45]
	s_cbranch_execz .LBB0_1243
	v_lshlrev_b64 v[18:19], 6, v[32:33]
	v_lshl_add_u64 v[18:19], s[0:1], 0, v[18:19]
	v_lshl_add_u64 v[18:19], s[26:27], 2, v[18:19]
	s_lshl_b32 s6, s37, 2
	v_lshl_add_u64 v[18:19], v[18:19], 0, s[6:7]
	s_waitcnt lgkmcnt(0)
	v_add_f32_e32 v16, v16, v17
	global_store_dword v[18:19], v16, off
.LBB0_1243:
	s_or_b64 exec, exec, s[8:9]
	v_add_u32_e32 v16, 0xb0, v146
	s_waitcnt lgkmcnt(0)
	v_ashrrev_i32_e32 v17, 31, v16
	v_lshlrev_b64 v[18:19], 10, v[16:17]
	v_lshl_add_u64 v[18:19], v[18:19], 0, v[144:145]
	v_lshlrev_b64 v[22:23], 1, v[18:19]
	v_lshl_add_u64 v[24:25], s[34:35], 0, v[22:23]
	v_lshl_add_u64 v[22:23], s[96:97], 0, v[22:23]
	s_waitcnt vmcnt(15)
	v_mov_b32_e32 v18, v228
	v_mov_b32_e32 v19, v229
	v_mov_b32_e32 v20, v230
	v_mov_b32_e32 v21, v231
	v_lshlrev_b32_e32 v26, 16, v18
	v_and_b32_e32 v27, 0xffff0000, v18
	v_lshlrev_b32_e32 v18, 16, v19
	v_and_b32_e32 v19, 0xffff0000, v19
	v_lshlrev_b32_e32 v28, 16, v20
	v_and_b32_e32 v29, 0xffff0000, v20
	v_lshlrev_b32_e32 v20, 16, v21
	v_and_b32_e32 v21, 0xffff0000, v21
	v_pk_add_f32 v[14:15], v[14:15], v[18:19]
	v_pk_add_f32 v[12:13], v[12:13], v[26:27]
	v_pk_add_f32 v[18:19], v[10:11], v[20:21]
	v_pk_add_f32 v[20:21], v[8:9], v[28:29]
	v_cvt_pk_bf16_f32 v8, v12, v13
	v_cvt_pk_bf16_f32 v9, v14, v15
	v_cvt_pk_bf16_f32 v10, v20, v21
	v_cvt_pk_bf16_f32 v11, v18, v19
	global_store_dwordx4 v[22:23], v[8:11], off
	s_nop 1
	v_mul_f32_e32 v8, v13, v13
	v_mul_f32_e32 v9, v15, v15
	v_fmac_f32_e32 v8, v12, v12
	v_fmac_f32_e32 v9, v14, v14
	v_add_f32_e32 v8, v8, v9
	v_mul_f32_e32 v9, v21, v21
	v_fmac_f32_e32 v9, v20, v20
	v_add_f32_e32 v8, v9, v8
	v_mul_f32_e32 v9, v19, v19
	v_fmac_f32_e32 v9, v18, v18
	v_add_f32_e32 v18, v9, v8
	s_waitcnt vmcnt(15)
	v_mov_b32_e32 v8, v232
	v_mov_b32_e32 v9, v233
	v_mov_b32_e32 v10, v234
	v_mov_b32_e32 v11, v235
	v_lshlrev_b32_e32 v12, 16, v8
	v_and_b32_e32 v13, 0xffff0000, v8
	v_lshlrev_b32_e32 v8, 16, v9
	v_and_b32_e32 v9, 0xffff0000, v9
	v_lshlrev_b32_e32 v14, 16, v10
	v_and_b32_e32 v15, 0xffff0000, v10
	v_lshlrev_b32_e32 v10, 16, v11
	v_and_b32_e32 v11, 0xffff0000, v11
	v_pk_add_f32 v[6:7], v[6:7], v[8:9]
	v_pk_add_f32 v[4:5], v[4:5], v[12:13]
	v_pk_add_f32 v[8:9], v[2:3], v[10:11]
	v_pk_add_f32 v[10:11], v[0:1], v[14:15]
	v_cvt_pk_bf16_f32 v0, v4, v5
	v_cvt_pk_bf16_f32 v1, v6, v7
	v_cvt_pk_bf16_f32 v2, v10, v11
	v_cvt_pk_bf16_f32 v3, v8, v9
	global_store_dwordx4 v[22:23], v[0:3], off offset:256
	s_nop 1
	v_mul_f32_e32 v0, v5, v5
	v_mul_f32_e32 v1, v7, v7
	v_fmac_f32_e32 v0, v4, v4
	v_fmac_f32_e32 v1, v6, v6
	v_add_f32_e32 v0, v0, v1
	v_mul_f32_e32 v1, v11, v11
	v_fmac_f32_e32 v1, v10, v10
	v_add_f32_e32 v0, v1, v0
	v_mul_f32_e32 v1, v9, v9
	v_fmac_f32_e32 v1, v8, v8
	v_add_f32_e32 v0, v1, v0
	v_add_f32_e32 v0, v18, v0
	ds_bpermute_b32 v1, v198, v0
	s_waitcnt lgkmcnt(0)
	v_add_f32_e32 v0, v0, v1
	ds_bpermute_b32 v1, v199, v0
	s_and_saveexec_b64 s[8:9], s[44:45]
	s_cbranch_execz .LBB0_1245
	v_lshlrev_b64 v[2:3], 6, v[16:17]
	v_lshl_add_u64 v[2:3], s[0:1], 0, v[2:3]
	v_lshl_add_u64 v[2:3], s[26:27], 2, v[2:3]
	s_lshl_b32 s6, s37, 2
	v_lshl_add_u64 v[2:3], v[2:3], 0, s[6:7]
	s_waitcnt lgkmcnt(0)
	v_add_f32_e32 v0, v0, v1
	global_store_dword v[2:3], v0, off

.LBB0_1402:
	v_lshl_add_u32 v148, s30, 8, v150
	v_lshl_add_u32 v146, s45, 8, v152
	v_ashrrev_i32_e32 v149, 31, v148
	v_ashrrev_i32_e32 v147, 31, v146
	v_lshlrev_b64 v[144:145], 10, v[148:149]
	v_lshl_add_u64 v[144:145], v[144:145], 0, v[146:147]
	v_lshlrev_b32_e32 v172, 1, v144
	global_load_dwordx4 v[168:171], v172, s[96:97]
	s_nop 0
	global_load_dwordx4 v[172:175], v172, s[96:97] offset:256
	v_lshlrev_b32_e32 v180, 1, v144
	v_add_u32_e32 v180, 0x8000, v180
	global_load_dwordx4 v[176:179], v180, s[96:97]
	s_nop 0
	global_load_dwordx4 v[180:183], v180, s[96:97] offset:256
	v_lshlrev_b32_e32 v188, 1, v144
	v_add_u32_e32 v188, 0x10000, v188
	global_load_dwordx4 v[184:187], v188, s[96:97]
	s_nop 0
	global_load_dwordx4 v[188:191], v188, s[96:97] offset:256
	v_lshlrev_b32_e32 v204, 1, v144
	v_add_u32_e32 v204, 0x18000, v204
	global_load_dwordx4 v[200:203], v204, s[96:97]
	s_nop 0
	global_load_dwordx4 v[204:207], v204, s[96:97] offset:256
	v_lshlrev_b32_e32 v212, 1, v144
	v_add_u32_e32 v212, 0x40000, v212
	global_load_dwordx4 v[208:211], v212, s[96:97]
	s_nop 0
	global_load_dwordx4 v[212:215], v212, s[96:97] offset:256
	v_lshlrev_b32_e32 v220, 1, v144
	v_add_u32_e32 v220, 0x48000, v220
	global_load_dwordx4 v[216:219], v220, s[96:97]
	s_nop 0
	global_load_dwordx4 v[220:223], v220, s[96:97] offset:256
	v_lshlrev_b32_e32 v228, 1, v144
	v_add_u32_e32 v228, 0x50000, v228
	global_load_dwordx4 v[224:227], v228, s[96:97]
	s_nop 0
	global_load_dwordx4 v[228:231], v228, s[96:97] offset:256
	v_lshlrev_b32_e32 v236, 1, v144
	v_add_u32_e32 v236, 0x58000, v236
	global_load_dwordx4 v[232:235], v236, s[96:97]
	s_nop 0
	global_load_dwordx4 v[236:239], v236, s[96:97] offset:256
	v_lshl_add_u64 v[160:161], v[144:145], 1, s[96:97]
	v_lshl_add_u64 v[162:163], v[144:145], 2, s[90:91]
	s_andn2_b64 vcc, exec, s[0:1]
	s_mov_b64 s[0:1], -1
	s_waitcnt vmcnt(15)
	v_mov_b32_e32 v156, v168
	v_mov_b32_e32 v157, v169
	v_mov_b32_e32 v158, v170
	v_mov_b32_e32 v159, v171
	v_lshlrev_b32_e32 v164, 16, v156
	v_and_b32_e32 v165, 0xffff0000, v156
	v_lshlrev_b32_e32 v156, 16, v157
	v_and_b32_e32 v157, 0xffff0000, v157
	v_lshlrev_b32_e32 v166, 16, v158
	v_and_b32_e32 v167, 0xffff0000, v158
	v_lshlrev_b32_e32 v158, 16, v159
	v_and_b32_e32 v159, 0xffff0000, v159
	v_pk_add_f32 v[126:127], v[126:127], v[156:157]
	v_pk_add_f32 v[124:125], v[124:125], v[164:165]
	v_pk_add_f32 v[122:123], v[122:123], v[158:159]
	v_pk_add_f32 v[120:121], v[120:121], v[166:167]
	global_store_dwordx4 v[162:163], v[124:127], off nt
	global_store_dwordx4 v[162:163], v[120:123], off offset:16 nt
	v_or_b32_e32 v124, 16, v148
	v_ashrrev_i32_e32 v125, 31, v124
	v_lshlrev_b64 v[124:125], 10, v[124:125]
	v_lshl_add_u64 v[124:125], v[124:125], 0, v[146:147]
	v_lshl_add_u64 v[126:127], v[124:125], 1, s[96:97]
	s_waitcnt vmcnt(15)
	v_mov_b32_e32 v120, v172
	v_mov_b32_e32 v121, v173
	v_mov_b32_e32 v122, v174
	v_mov_b32_e32 v123, v175
	v_lshlrev_b32_e32 v156, 16, v120
	v_and_b32_e32 v157, 0xffff0000, v120
	v_lshlrev_b32_e32 v120, 16, v121
	v_and_b32_e32 v121, 0xffff0000, v121
	v_lshlrev_b32_e32 v158, 16, v122
	v_and_b32_e32 v159, 0xffff0000, v122
	v_lshlrev_b32_e32 v122, 16, v123
	v_and_b32_e32 v123, 0xffff0000, v123
	v_pk_add_f32 v[118:119], v[118:119], v[120:121]
	v_pk_add_f32 v[116:117], v[116:117], v[156:157]
	v_pk_add_f32 v[114:115], v[114:115], v[122:123]
	v_pk_add_f32 v[112:113], v[112:113], v[158:159]
	global_store_dwordx4 v[162:163], v[116:119], off offset:512 nt
	global_store_dwordx4 v[162:163], v[112:115], off offset:528 nt
	v_lshl_add_u64 v[116:117], v[124:125], 2, s[90:91]
	s_waitcnt vmcnt(15)
	v_mov_b32_e32 v112, v176
	v_mov_b32_e32 v113, v177
	v_mov_b32_e32 v114, v178
	v_mov_b32_e32 v115, v179
	v_lshlrev_b32_e32 v118, 16, v112
	v_and_b32_e32 v119, 0xffff0000, v112
	v_lshlrev_b32_e32 v112, 16, v113
	v_and_b32_e32 v113, 0xffff0000, v113
	v_lshlrev_b32_e32 v120, 16, v114
	v_and_b32_e32 v121, 0xffff0000, v114
	v_lshlrev_b32_e32 v114, 16, v115
	v_and_b32_e32 v115, 0xffff0000, v115
	v_pk_add_f32 v[110:111], v[110:111], v[112:113]
	v_pk_add_f32 v[108:109], v[108:109], v[118:119]
	v_pk_add_f32 v[106:107], v[106:107], v[114:115]
	v_pk_add_f32 v[104:105], v[104:105], v[120:121]
	global_store_dwordx4 v[116:117], v[108:111], off nt
	global_store_dwordx4 v[116:117], v[104:107], off offset:16 nt
	v_or_b32_e32 v108, 32, v148
	v_ashrrev_i32_e32 v109, 31, v108
	v_lshlrev_b64 v[108:109], 10, v[108:109]
	v_lshl_add_u64 v[108:109], v[108:109], 0, v[146:147]
	v_lshl_add_u64 v[110:111], v[108:109], 1, s[96:97]
	s_waitcnt vmcnt(15)
	v_mov_b32_e32 v104, v180
	v_mov_b32_e32 v105, v181
	v_mov_b32_e32 v106, v182
	v_mov_b32_e32 v107, v183
	v_lshlrev_b32_e32 v112, 16, v104
	v_and_b32_e32 v113, 0xffff0000, v104
	v_lshlrev_b32_e32 v104, 16, v105
	v_and_b32_e32 v105, 0xffff0000, v105
	v_lshlrev_b32_e32 v114, 16, v106
	v_and_b32_e32 v115, 0xffff0000, v106
	v_lshlrev_b32_e32 v106, 16, v107
	v_and_b32_e32 v107, 0xffff0000, v107
	v_pk_add_f32 v[102:103], v[102:103], v[104:105]
	v_pk_add_f32 v[100:101], v[100:101], v[112:113]
	v_pk_add_f32 v[98:99], v[98:99], v[106:107]
	v_pk_add_f32 v[96:97], v[96:97], v[114:115]
	global_store_dwordx4 v[116:117], v[100:103], off offset:512 nt
	global_store_dwordx4 v[116:117], v[96:99], off offset:528 nt
	v_lshl_add_u64 v[100:101], v[108:109], 2, s[90:91]
	s_waitcnt vmcnt(15)
	v_mov_b32_e32 v96, v184
	v_mov_b32_e32 v97, v185
	v_mov_b32_e32 v98, v186
	v_mov_b32_e32 v99, v187
	v_lshlrev_b32_e32 v102, 16, v96
	v_and_b32_e32 v103, 0xffff0000, v96
	v_lshlrev_b32_e32 v96, 16, v97
	v_and_b32_e32 v97, 0xffff0000, v97
	v_lshlrev_b32_e32 v104, 16, v98
	v_and_b32_e32 v105, 0xffff0000, v98
	v_lshlrev_b32_e32 v98, 16, v99
	v_and_b32_e32 v99, 0xffff0000, v99
	v_pk_add_f32 v[94:95], v[94:95], v[96:97]
	v_pk_add_f32 v[92:93], v[92:93], v[102:103]
	v_pk_add_f32 v[90:91], v[90:91], v[98:99]
	v_pk_add_f32 v[88:89], v[88:89], v[104:105]
	global_store_dwordx4 v[100:101], v[92:95], off nt
	global_store_dwordx4 v[100:101], v[88:91], off offset:16 nt
	v_or_b32_e32 v92, 48, v148
	v_ashrrev_i32_e32 v93, 31, v92
	v_lshlrev_b64 v[92:93], 10, v[92:93]
	v_lshl_add_u64 v[92:93], v[92:93], 0, v[146:147]
	v_lshl_add_u64 v[94:95], v[92:93], 1, s[96:97]
	s_waitcnt vmcnt(15)
	v_mov_b32_e32 v88, v188
	v_mov_b32_e32 v89, v189
	v_mov_b32_e32 v90, v190
	v_mov_b32_e32 v91, v191
	v_lshlrev_b32_e32 v96, 16, v88
	v_and_b32_e32 v97, 0xffff0000, v88
	v_lshlrev_b32_e32 v88, 16, v89
	v_and_b32_e32 v89, 0xffff0000, v89
	v_lshlrev_b32_e32 v98, 16, v90
	v_and_b32_e32 v99, 0xffff0000, v90
	v_lshlrev_b32_e32 v90, 16, v91
	v_and_b32_e32 v91, 0xffff0000, v91
	v_pk_add_f32 v[86:87], v[86:87], v[88:89]
	v_pk_add_f32 v[84:85], v[84:85], v[96:97]
	v_pk_add_f32 v[82:83], v[82:83], v[90:91]
	v_pk_add_f32 v[80:81], v[80:81], v[98:99]
	global_store_dwordx4 v[100:101], v[84:87], off offset:512 nt
	global_store_dwordx4 v[100:101], v[80:83], off offset:528 nt
	v_lshl_add_u64 v[84:85], v[92:93], 2, s[90:91]
	s_waitcnt vmcnt(15)
	v_mov_b32_e32 v80, v200
	v_mov_b32_e32 v81, v201
	v_mov_b32_e32 v82, v202
	v_mov_b32_e32 v83, v203
	v_lshlrev_b32_e32 v86, 16, v80
	v_and_b32_e32 v87, 0xffff0000, v80
	v_lshlrev_b32_e32 v80, 16, v81
	v_and_b32_e32 v81, 0xffff0000, v81
	v_lshlrev_b32_e32 v88, 16, v82
	v_and_b32_e32 v89, 0xffff0000, v82
	v_lshlrev_b32_e32 v82, 16, v83
	v_and_b32_e32 v83, 0xffff0000, v83
	v_pk_add_f32 v[78:79], v[78:79], v[80:81]
	v_pk_add_f32 v[76:77], v[76:77], v[86:87]
	v_pk_add_f32 v[74:75], v[74:75], v[82:83]
	v_pk_add_f32 v[72:73], v[72:73], v[88:89]
	global_store_dwordx4 v[84:85], v[76:79], off nt
	global_store_dwordx4 v[84:85], v[72:75], off offset:16 nt
	v_lshl_add_u64 v[76:77], v[144:145], 0, s[12:13]
	v_lshl_add_u64 v[78:79], v[76:77], 1, s[96:97]
	s_waitcnt vmcnt(15)
	v_mov_b32_e32 v72, v204
	v_mov_b32_e32 v73, v205
	v_mov_b32_e32 v74, v206
	v_mov_b32_e32 v75, v207
	v_lshlrev_b32_e32 v80, 16, v72
	v_and_b32_e32 v81, 0xffff0000, v72
	v_lshlrev_b32_e32 v72, 16, v73
	v_and_b32_e32 v73, 0xffff0000, v73
	v_lshlrev_b32_e32 v82, 16, v74
	v_and_b32_e32 v83, 0xffff0000, v74
	v_lshlrev_b32_e32 v74, 16, v75
	v_and_b32_e32 v75, 0xffff0000, v75
	v_pk_add_f32 v[70:71], v[70:71], v[72:73]
	v_pk_add_f32 v[68:69], v[68:69], v[80:81]
	v_pk_add_f32 v[66:67], v[66:67], v[74:75]
	v_pk_add_f32 v[64:65], v[64:65], v[82:83]
	global_store_dwordx4 v[84:85], v[68:71], off offset:512 nt
	global_store_dwordx4 v[84:85], v[64:67], off offset:528 nt
	v_lshl_add_u64 v[68:69], v[76:77], 2, s[90:91]
	s_waitcnt vmcnt(15)
	v_mov_b32_e32 v64, v208
	v_mov_b32_e32 v65, v209
	v_mov_b32_e32 v66, v210
	v_mov_b32_e32 v67, v211
	v_lshlrev_b32_e32 v70, 16, v64
	v_and_b32_e32 v71, 0xffff0000, v64
	v_lshlrev_b32_e32 v64, 16, v65
	v_and_b32_e32 v65, 0xffff0000, v65
	v_lshlrev_b32_e32 v72, 16, v66
	v_and_b32_e32 v73, 0xffff0000, v66
	v_lshlrev_b32_e32 v66, 16, v67
	v_and_b32_e32 v67, 0xffff0000, v67
	v_pk_add_f32 v[62:63], v[62:63], v[64:65]
	v_pk_add_f32 v[60:61], v[60:61], v[70:71]
	v_pk_add_f32 v[58:59], v[58:59], v[66:67]
	v_pk_add_f32 v[56:57], v[56:57], v[72:73]
	global_store_dwordx4 v[68:69], v[60:63], off nt
	global_store_dwordx4 v[68:69], v[56:59], off offset:16 nt
	v_lshl_add_u64 v[60:61], v[144:145], 0, s[14:15]
	v_lshl_add_u64 v[62:63], v[60:61], 1, s[96:97]
	s_waitcnt vmcnt(15)
	v_mov_b32_e32 v56, v212
	v_mov_b32_e32 v57, v213
	v_mov_b32_e32 v58, v214
	v_mov_b32_e32 v59, v215
	v_lshlrev_b32_e32 v64, 16, v56
	v_and_b32_e32 v65, 0xffff0000, v56
	v_lshlrev_b32_e32 v56, 16, v57
	v_and_b32_e32 v57, 0xffff0000, v57
	v_lshlrev_b32_e32 v66, 16, v58
	v_and_b32_e32 v67, 0xffff0000, v58
	v_lshlrev_b32_e32 v58, 16, v59
	v_and_b32_e32 v59, 0xffff0000, v59
	v_pk_add_f32 v[54:55], v[54:55], v[56:57]
	v_pk_add_f32 v[52:53], v[52:53], v[64:65]
	v_pk_add_f32 v[50:51], v[50:51], v[58:59]
	v_pk_add_f32 v[48:49], v[48:49], v[66:67]
	global_store_dwordx4 v[68:69], v[52:55], off offset:512 nt
	global_store_dwordx4 v[68:69], v[48:51], off offset:528 nt
	v_lshl_add_u64 v[52:53], v[60:61], 2, s[90:91]
	s_waitcnt vmcnt(15)
	v_mov_b32_e32 v48, v216
	v_mov_b32_e32 v49, v217
	v_mov_b32_e32 v50, v218
	v_mov_b32_e32 v51, v219
	v_lshlrev_b32_e32 v54, 16, v48
	v_and_b32_e32 v55, 0xffff0000, v48
	v_lshlrev_b32_e32 v48, 16, v49
	v_and_b32_e32 v49, 0xffff0000, v49
	v_lshlrev_b32_e32 v56, 16, v50
	v_and_b32_e32 v57, 0xffff0000, v50
	v_lshlrev_b32_e32 v50, 16, v51
	v_and_b32_e32 v51, 0xffff0000, v51
	v_pk_add_f32 v[46:47], v[46:47], v[48:49]
	v_pk_add_f32 v[44:45], v[44:45], v[54:55]
	v_pk_add_f32 v[42:43], v[42:43], v[50:51]
	v_pk_add_f32 v[40:41], v[40:41], v[56:57]
	global_store_dwordx4 v[52:53], v[44:47], off nt
	global_store_dwordx4 v[52:53], v[40:43], off offset:16 nt
	v_lshl_add_u64 v[44:45], v[144:145], 0, s[16:17]
	v_lshl_add_u64 v[46:47], v[44:45], 1, s[96:97]
	s_waitcnt vmcnt(15)
	v_mov_b32_e32 v40, v220
	v_mov_b32_e32 v41, v221
	v_mov_b32_e32 v42, v222
	v_mov_b32_e32 v43, v223
	v_lshlrev_b32_e32 v48, 16, v40
	v_and_b32_e32 v49, 0xffff0000, v40
	v_lshlrev_b32_e32 v40, 16, v41
	v_and_b32_e32 v41, 0xffff0000, v41
	v_lshlrev_b32_e32 v50, 16, v42
	v_and_b32_e32 v51, 0xffff0000, v42
	v_lshlrev_b32_e32 v42, 16, v43
	v_and_b32_e32 v43, 0xffff0000, v43
	v_pk_add_f32 v[38:39], v[38:39], v[40:41]
	v_pk_add_f32 v[36:37], v[36:37], v[48:49]
	v_pk_add_f32 v[34:35], v[34:35], v[42:43]
	v_pk_add_f32 v[32:33], v[32:33], v[50:51]
	global_store_dwordx4 v[52:53], v[36:39], off offset:512 nt
	global_store_dwordx4 v[52:53], v[32:35], off offset:528 nt
	v_lshl_add_u64 v[36:37], v[44:45], 2, s[90:91]
	s_waitcnt vmcnt(15)
	v_mov_b32_e32 v32, v224
	v_mov_b32_e32 v33, v225
	v_mov_b32_e32 v34, v226
	v_mov_b32_e32 v35, v227
	v_lshlrev_b32_e32 v38, 16, v32
	v_and_b32_e32 v39, 0xffff0000, v32
	v_lshlrev_b32_e32 v32, 16, v33
	v_and_b32_e32 v33, 0xffff0000, v33
	v_lshlrev_b32_e32 v40, 16, v34
	v_and_b32_e32 v41, 0xffff0000, v34
	v_lshlrev_b32_e32 v34, 16, v35
	v_and_b32_e32 v35, 0xffff0000, v35
	v_pk_add_f32 v[30:31], v[30:31], v[32:33]
	v_pk_add_f32 v[28:29], v[28:29], v[38:39]
	v_pk_add_f32 v[26:27], v[26:27], v[34:35]
	v_pk_add_f32 v[24:25], v[24:25], v[40:41]
	global_store_dwordx4 v[36:37], v[28:31], off nt
	global_store_dwordx4 v[36:37], v[24:27], off offset:16 nt
	v_lshl_add_u64 v[28:29], v[144:145], 0, s[20:21]
	v_lshl_add_u64 v[30:31], v[28:29], 1, s[96:97]
	s_waitcnt vmcnt(15)
	v_mov_b32_e32 v24, v228
	v_mov_b32_e32 v25, v229
	v_mov_b32_e32 v26, v230
	v_mov_b32_e32 v27, v231
	v_lshlrev_b32_e32 v32, 16, v24
	v_and_b32_e32 v33, 0xffff0000, v24
	v_lshlrev_b32_e32 v24, 16, v25
	v_and_b32_e32 v25, 0xffff0000, v25
	v_lshlrev_b32_e32 v34, 16, v26
	v_and_b32_e32 v35, 0xffff0000, v26
	v_lshlrev_b32_e32 v26, 16, v27
	v_and_b32_e32 v27, 0xffff0000, v27
	v_pk_add_f32 v[22:23], v[22:23], v[24:25]
	v_pk_add_f32 v[20:21], v[20:21], v[32:33]
	v_pk_add_f32 v[18:19], v[18:19], v[26:27]
	v_pk_add_f32 v[16:17], v[16:17], v[34:35]
	global_store_dwordx4 v[36:37], v[20:23], off offset:512 nt
	global_store_dwordx4 v[36:37], v[16:19], off offset:528 nt
	v_lshl_add_u64 v[20:21], v[28:29], 2, s[90:91]
	s_waitcnt vmcnt(15)
	v_mov_b32_e32 v16, v232
	v_mov_b32_e32 v17, v233
	v_mov_b32_e32 v18, v234
	v_mov_b32_e32 v19, v235
	v_lshlrev_b32_e32 v22, 16, v16
	v_and_b32_e32 v23, 0xffff0000, v16
	v_lshlrev_b32_e32 v16, 16, v17
	v_and_b32_e32 v17, 0xffff0000, v17
	v_lshlrev_b32_e32 v24, 16, v18
	v_and_b32_e32 v25, 0xffff0000, v18
	v_lshlrev_b32_e32 v18, 16, v19
	v_and_b32_e32 v19, 0xffff0000, v19
	v_pk_add_f32 v[14:15], v[14:15], v[16:17]
	v_pk_add_f32 v[12:13], v[12:13], v[22:23]
	v_pk_add_f32 v[10:11], v[10:11], v[18:19]
	v_pk_add_f32 v[8:9], v[8:9], v[24:25]
	global_store_dwordx4 v[20:21], v[12:15], off nt
	global_store_dwordx4 v[20:21], v[8:11], off offset:16 nt
	s_waitcnt vmcnt(15)
	v_mov_b32_e32 v8, v236
	v_mov_b32_e32 v9, v237
	v_mov_b32_e32 v10, v238
	v_mov_b32_e32 v11, v239
	v_lshlrev_b32_e32 v12, 16, v8
	v_and_b32_e32 v13, 0xffff0000, v8
	v_lshlrev_b32_e32 v8, 16, v9
	v_and_b32_e32 v9, 0xffff0000, v9
	v_lshlrev_b32_e32 v14, 16, v10
	v_and_b32_e32 v15, 0xffff0000, v10
	v_lshlrev_b32_e32 v10, 16, v11
	v_and_b32_e32 v11, 0xffff0000, v11
	v_pk_add_f32 v[6:7], v[6:7], v[8:9]
	v_pk_add_f32 v[4:5], v[4:5], v[12:13]
	v_pk_add_f32 v[2:3], v[2:3], v[10:11]
	v_pk_add_f32 v[0:1], v[0:1], v[14:15]
	global_store_dwordx4 v[20:21], v[4:7], off offset:512 nt
	global_store_dwordx4 v[20:21], v[0:3], off offset:528 nt
	s_cbranch_vccnz .LBB0_1391
	s_andn2_b64 vcc, exec, s[6:7]
	s_cbranch_vccnz .LBB0_1390
	s_barrier
	s_branch .LBB0_1390
